# A->B seam: grid barrier replaced by an 8-workgroup (same XCD) arrive/wait on the DILP partials, with placement check and grid-barrier fallback
# speedup vs baseline: 1.0069x; 1.0057x over previous
_Z10fwd_kernel6Params:
	s_load_dwordx8 s[36:43], s[0:1], 0x40
	s_load_dword s3, s[0:1], 0x60
	s_add_u32 s6, s0, 0x58
	v_and_b32_e32 v1, 0x3ff, v0
	s_addc_u32 s7, s1, 0
	v_cmp_gt_u32_e32 vcc, 16, v1
	s_and_saveexec_b64 s[4:5], vcc
	v_lshl_add_u32 v2, v1, 2, 0
	v_add_u32_e32 v2, 0x23fc0, v2
	v_mov_b32_e32 v3, 0
	ds_write_b32 v2, v3
	s_or_b64 exec, exec, s[4:5]
	s_waitcnt lgkmcnt(0)
	s_add_u32 s96, s40, 0x4000
	s_barrier
	s_addc_u32 s97, s41, 0
	s_getreg_b32 s10, hwreg(HW_REG_XCC_ID, 0, 4)
	v_cmp_eq_u32_e64 s[64:65], 0, v1
	s_and_saveexec_b64 s[4:5], s[64:65]
	s_cbranch_execz .LBB0_5
	s_mov_b64 s[8:9], exec
	v_mbcnt_lo_u32_b32 v2, s8, 0
	v_mbcnt_hi_u32_b32 v2, s9, v2
	v_cmp_eq_u32_e32 vcc, 0, v2
	s_and_b64 s[12:13], exec, vcc
	s_mov_b64 exec, s[12:13]
	s_cbranch_execz .LBB0_5
	s_and_b32 s11, s2, 7
	s_and_b32 s14, s10, 15
	s_cmp_eq_u32 s11, s14
	s_cbranch_scc1 .Lplace_ok
	v_mov_b32_e32 v2, 0
	v_mov_b32_e32 v3, 1
	global_atomic_add v2, v3, s[96:97] offset:256
.Lplace_ok:
	s_lshl_b32 s10, s10, 8
	s_and_b32 s10, s10, 0xf00
	s_bcnt1_i32_b64 s8, s[8:9]
	v_mov_b32_e32 v2, s10
	v_mov_b32_e32 v3, s8
	global_atomic_add v2, v3, s[96:97] offset:1024

.LBB0_127:
	s_lshr_b32 s1, s42, 3
	s_mul_i32 s1, s1, s4
	s_and_b32 s0, s42, 7
	s_add_i32 s1, s1, s5
	s_lshl_b32 s5, s51, 7
	s_cmp_eq_u32 s0, 0
	s_cselect_b32 s66, s1, s2
	s_mul_hi_i32 s6, s66, 0x2aaaaaab
	s_ashr_i32 s10, s6, 7
	s_lshr_b32 s7, s6, 31
	s_add_i32 s10, s10, s7
	s_mul_i32 s0, s10, 0x300
	s_sub_i32 s9, s66, s0
	s_mul_i32 s0, s9, 0x2aab
	s_lshr_b32 s1, s0, 31
	s_ashr_i32 s0, s0, 19
	s_add_i32 s0, s0, s1
	s_mul_i32 s1, s0, 48
	s_sub_i32 s1, s9, s1
	s_sext_i32_i16 s1, s1
	s_add_i32 s8, s66, 0x2ff
	s_and_b32 s12, s1, 7
	s_and_b32 s11, s1, 1
	s_cmp_lt_i32 s51, 0
	s_mul_i32 s13, s51, 0x81
	s_movk_i32 s67, 0x1c1
	s_cselect_b32 s4, s67, 0x1c0
	s_cselect_b32 s5, s13, s5
	s_cmpk_lt_u32 s8, 0x5ff
	s_cselect_b32 s14, s11, s12
	s_bfe_u32 s11, s1, 0x20001
	s_sext_i32_i16 s13, s9
	s_cmpk_lt_u32 s8, 0x5ff
	s_mul_i32 s15, s13, 0x2aab
	s_cselect_b32 s13, s11, 0
	s_lshr_b32 s11, s15, 31
	s_ashr_i32 s15, s15, 19
	s_add_i32 s15, s15, s11
	s_mul_i32 s11, s15, 48
	s_sub_i32 s9, s9, s11
	s_sext_i32_i16 s11, s9
	s_and_b32 s16, s11, 7
	s_and_b32 s9, s11, 1
	s_cmpk_lt_u32 s8, 0x5ff
	s_cselect_b32 s17, s9, s16
	s_bfe_u32 s9, s11, 0x20001
	s_cmpk_lt_u32 s8, 0x5ff
	s_mulk_i32 s9, 0x3800
	s_cselect_b32 s9, s9, 0
	s_cmpk_lt_i32 s2, 0xe00
	s_cselect_b64 s[18:19], -1, 0
	s_add_u32 s72, s40, 0x4200
	s_addc_u32 s73, s41, 0
	s_add_u32 s74, s40, 0x4400
	s_addc_u32 s75, s41, 0
	s_add_u32 s76, s40, 0x4500
	s_addc_u32 s77, s41, 0
	s_add_u32 s90, s40, 0x4600
	s_addc_u32 s91, s41, 0
	s_add_u32 s26, s40, 0x4700
	s_mul_i32 s8, s43, s42
	v_writelane_b32 v252, s9, 21
	s_addc_u32 s27, s41, 0
	v_writelane_b32 v252, s18, 22
	s_mul_i32 s70, s8, s3
	s_add_u32 s8, s40, 0x4800
	v_writelane_b32 v252, s19, 23
	s_addc_u32 s9, s41, 0
	v_writelane_b32 v252, s8, 24
	s_mul_i32 s4, s51, s4
	s_mov_b32 s99, 0
	v_writelane_b32 v252, s9, 25
	s_add_u32 s8, s40, 0x4900
	s_addc_u32 s9, s41, 0
	v_writelane_b32 v252, s8, 26
	s_mov_b32 s44, 0xe000
	s_movk_i32 s47, 0x800
	v_writelane_b32 v252, s9, 27
	s_add_u32 s8, s40, 0x4a00
	s_addc_u32 s9, s41, 0
	v_writelane_b32 v252, s8, 28
	s_movk_i32 s83, 0x200
	s_movk_i32 s33, 0x81
	v_writelane_b32 v252, s9, 29
	s_add_u32 s8, s40, 0x4b00
	s_addc_u32 s9, s41, 0
	v_writelane_b32 v252, s8, 30
	s_movk_i32 s43, 0x3800
	s_movk_i32 s94, 0x600
	v_writelane_b32 v252, s9, 31
	s_add_u32 s8, s40, 0x4c00
	s_addc_u32 s9, s41, 0
	v_writelane_b32 v252, s8, 32
	v_mov_b32_e32 v1, 0
	v_mov_b32_e32 v205, 0x2000
	v_writelane_b32 v252, s9, 33
	s_add_u32 s8, s40, 0x4d00
	s_addc_u32 s9, s41, 0
	v_writelane_b32 v252, s8, 34
	v_mov_b32_e32 v206, 1
	s_mov_b64 s[92:93], 0x600
	v_writelane_b32 v252, s9, 35
	s_add_u32 s8, s40, 0x4e00
	s_addc_u32 s9, s41, 0
	v_writelane_b32 v252, s8, 36
	v_mbcnt_hi_u32_b32 v207, -1, v146
	v_mov_b32_e32 v208, 0x358637bd
	v_writelane_b32 v252, s9, 37
	s_add_u32 s8, s40, 0x4f00
	s_addc_u32 s9, s41, 0
	v_writelane_b32 v252, s8, 38
	v_mov_b32_e32 v209, 0x260
	v_mov_b64_e32 v[148:149], 0xe00
	v_writelane_b32 v252, s9, 39
	s_add_u32 s8, s40, 0x5000
	s_addc_u32 s9, s41, 0
	v_writelane_b32 v252, s8, 40
	v_mov_b64_e32 v[150:151], 0xdff
	v_mov_b32_e32 v210, 0xf149f2ca
	v_writelane_b32 v252, s9, 41
	s_add_u32 s8, s40, 0x5100
	s_addc_u32 s9, s41, 0
	v_writelane_b32 v252, s8, 42
	v_mov_b32_e32 v211, 0x3800
	v_mov_b32_e32 v212, 0x400
	v_writelane_b32 v252, s9, 43
	s_add_u32 s8, s40, 0x5200
	s_addc_u32 s9, s41, 0
	v_writelane_b32 v252, s8, 44
	v_mov_b32_e32 v213, 0x7e0
	v_mov_b32_e32 v214, 0x600
	v_writelane_b32 v252, s9, 45
	s_add_u32 s8, s40, 0x5300
	s_addc_u32 s9, s41, 0
	v_writelane_b32 v252, s8, 46
	v_mov_b64_e32 v[152:153], 0x400
	v_mov_b64_e32 v[154:155], 0x3ff
	v_writelane_b32 v252, s9, 47
	s_add_u32 s8, s40, 0x7400
	s_addc_u32 s9, s41, 0
	v_writelane_b32 v252, s8, 48
	s_nop 1
	v_writelane_b32 v252, s9, 49
	s_add_u32 s8, s40, 0x7500
	s_addc_u32 s9, s41, 0
	v_writelane_b32 v252, s8, 50
	s_lshl_b32 s3, s95, 2
	s_lshl_b32 s31, s95, 5
	v_writelane_b32 v252, s9, 51
	v_writelane_b32 v252, s3, 52
	s_lshl_b32 s3, s95, 1
	s_and_b32 s29, s3, 2
	s_lshl_b32 s3, s95, 10
	s_add_i32 s85, s3, 0
	s_add_i32 s30, s85, s3
	s_add_i32 s3, s85, 0x2000
	v_writelane_b32 v252, s3, 53
	s_add_i32 s3, s30, 0x400
	v_writelane_b32 v252, s3, 54
	s_add_i32 s3, s85, 0x4000
	v_writelane_b32 v252, s3, 55
	s_add_i32 s3, s85, 0x6000
	v_writelane_b32 v252, s3, 56
	s_add_i32 s3, s30, 0x4000
	v_writelane_b32 v252, s3, 57
	s_add_i32 s3, s30, 0x4400
	v_writelane_b32 v252, s3, 58
	s_add_i32 s3, s85, 0x8000
	v_writelane_b32 v252, s3, 59
	s_add_i32 s3, s85, 0xa000
	v_writelane_b32 v252, s3, 60
	s_add_i32 s3, s30, 0x8000
	v_writelane_b32 v252, s3, 61
	s_add_i32 s3, s30, 0x8400
	v_writelane_b32 v252, s3, 62
	s_add_i32 s3, s85, 0xc000
	v_writelane_b32 v252, s3, 63
	s_add_i32 s3, s85, 0xe000
	v_writelane_b32 v253, s3, 0
	s_add_i32 s3, s30, 0xc000
	v_writelane_b32 v253, s3, 1
	s_add_i32 s3, s30, 0xc400
	v_writelane_b32 v253, s3, 2
	s_and_b32 s3, s31, 0x60
	v_writelane_b32 v253, s3, 3
	s_mul_i32 s3, s95, 0x1200
	s_add_i32 s3, s3, 0
	s_add_i32 s3, s3, 0x1ae00
	v_writelane_b32 v253, s3, 4
	s_lshl_b32 s3, s95, 9
	s_lshr_b32 s8, s34, 8
	s_and_b32 s3, s3, 0x600
	v_writelane_b32 v253, s8, 5
	s_add_i32 s3, s3, s8
	s_bfe_u32 s84, s34, 0x20006
	s_lshl_b32 s28, s95, 3
	v_writelane_b32 v253, s3, 6
	s_add_i32 s3, s95, 4
	s_cmpk_lt_i32 s2, 0x400
	s_cselect_b64 s[8:9], -1, 0
	v_writelane_b32 v253, s8, 7
	s_add_i32 s4, s4, s50
	s_ashr_i32 s6, s6, 3
	v_writelane_b32 v253, s9, 8
	s_mul_hi_i32 s8, s4, 0x92492493
	s_add_i32 s8, s8, s4
	s_lshr_b32 s9, s8, 31
	s_ashr_i32 s8, s8, 7
	s_add_i32 s8, s8, s9
	s_mul_i32 s9, s8, 0xe0
	s_sub_i32 s9, s4, s9
	s_bfe_u32 s4, s9, 0x3001c
	s_add_i32 s18, s9, s4
	s_sext_i32_i16 s19, s18
	s_and_b32 s18, s18, 0xfff8
	s_sub_i32 s9, s9, s18
	s_lshl_b32 s8, s8, 3
	s_sext_i32_i16 s9, s9
	s_add_i32 s46, s8, s9
	s_ashr_i32 s8, s19, 3
	v_writelane_b32 v253, s8, 9
	s_ashr_i32 s8, s66, 3
	s_mul_hi_i32 s9, s8, 0x55555556
	s_lshr_b32 s18, s9, 31
	s_add_i32 s9, s9, s18
	s_mul_i32 s9, s9, 3
	s_sub_i32 s82, s8, s9
	s_ashr_i32 s8, s66, 5
	s_add_i32 s6, s6, s7
	s_ashr_i32 s9, s8, 31
	s_mul_i32 s7, s6, 48
	s_lshr_b32 s4, s19, 3
	s_lshl_b64 s[18:19], s[8:9], 21
	s_sub_i32 s20, s66, s7
	v_writelane_b32 v253, s18, 10
	s_lshl_b32 s7, s20, 2
	s_lshl_b32 s48, s42, 4
	v_writelane_b32 v253, s19, 11
	s_lshl_b32 s18, s66, 5
	s_and_b32 s19, s7, 28
	s_and_b32 s18, s18, 0x300
	v_sub_u32_e64 v0, s19, 1 clamp
	v_writelane_b32 v253, s18, 12
	v_readfirstlane_b32 s18, v0
	s_max_u32 s7, s19, 4
	s_min_u32 s18, s18, 24
	s_sub_i32 s18, s18, s7
	s_lshl_b32 s18, s18, 1
	s_add_i32 s18, s18, 24
	s_lshl_b32 s7, s7, 6
	v_writelane_b32 v253, s18, 13
	s_add_i32 s18, s7, 0xffffff00
	s_ashr_i32 s7, s6, 31
	s_lshl_b64 s[24:25], s[6:7], 11
	s_add_u32 s7, s24, s18
	v_writelane_b32 v253, s24, 14
	s_addc_u32 s18, s25, 0
	s_mul_hi_u32 s21, s7, 0x3800
	s_mulk_i32 s18, 0x3800
	v_writelane_b32 v253, s25, 15
	s_add_i32 s18, s21, s18
	v_writelane_b32 v253, s18, 16
	s_lshl_b32 s18, s20, 4
	s_and_b32 s45, s18, 0xffffff80
	s_add_i32 s98, s45, 0x300
	s_lshl_b32 s11, s11, 4
	s_lshl_b64 s[24:25], s[98:99], 1
	s_and_b32 s11, s11, 0xffffff80
	v_writelane_b32 v253, s24, 17
	s_add_i32 s98, s11, 0xf00
	v_add_co_u32_e64 v0, s[10:11], s10, 1
	v_writelane_b32 v253, s25, 18
	s_lshl_b64 s[24:25], s[98:99], 1
	v_writelane_b32 v253, s24, 19
	s_lshl_b32 s17, s17, 8
	v_cmp_ne_u32_e64 s[52:53], 2, v0
	v_writelane_b32 v253, s25, 20
	s_and_b64 s[24:25], s[10:11], exec
	v_writelane_b32 v253, s17, 21
	s_cselect_b32 s17, s47, 0x200
	s_cselect_b32 s24, 0x3800, s44
	s_add_i32 s18, s66, s42
	v_writelane_b32 v253, s17, 22
	s_cmp_eq_u32 s82, 1
	s_cselect_b32 s17, 1, 2
	s_cselect_b32 s21, s83, 0x600
	v_writelane_b32 v253, s52, 23
	s_cmp_eq_u32 s82, 0
	s_cselect_b32 s17, 0, s17
	v_writelane_b32 v253, s53, 24
	v_writelane_b32 v253, s17, 25
	s_mulk_i32 s7, 0x3800
	v_writelane_b32 v253, s7, 26
	s_mul_hi_i32 s7, s15, 0x1c00000
	v_writelane_b32 v253, s7, 27
	s_mul_i32 s7, s15, 0x1c00000
	v_writelane_b32 v253, s7, 28
	s_mov_b32 s25, s99
	v_writelane_b32 v253, s24, 29
	s_mul_i32 s7, s16, 0x7000
	s_nop 0
	v_writelane_b32 v253, s25, 30
	v_writelane_b32 v253, s7, 31
	s_cselect_b32 s7, 0x300, s21
	s_cmp_ge_i32 s18, s7
	s_cselect_b64 s[16:17], -1, 0
	s_and_b64 s[24:25], s[16:17], exec
	v_cndmask_b32_e64 v0, 0, 1, s[16:17]
	s_cselect_b32 s24, s66, s18
	v_readfirstlane_b32 s7, v0
	s_cmp_lg_u64 s[16:17], 0
	s_nop 0
	v_writelane_b32 v253, s7, 32
	s_addc_u32 s7, s82, 0
	s_cmp_lg_u64 s[16:17], 0
	s_addc_u32 s15, s82, -3
	s_cmp_gt_i32 s7, 2
	s_cselect_b32 s7, s15, s7
	s_cmp_eq_u32 s7, 1
	s_cselect_b32 s15, 1, 2
	s_cmp_lg_u32 s7, 0
	s_cselect_b32 s7, s15, 0
	s_ashr_i32 s16, s24, 5
	s_ashr_i32 s17, s16, 31
	v_writelane_b32 v253, s7, 33
	s_lshl_b64 s[16:17], s[16:17], 21
	v_writelane_b32 v253, s16, 34
	s_lshl_b32 s7, s24, 5
	s_and_b32 s7, s7, 0x300
	v_writelane_b32 v253, s17, 35
	v_writelane_b32 v253, s7, 36
	s_mul_hi_i32 s7, s24, 0x2aaaaaab
	s_ashr_i32 s15, s7, 3
	s_lshr_b32 s18, s7, 31
	s_add_i32 s16, s15, s18
	s_mul_i32 s15, s16, 48
	s_sub_i32 s15, s24, s15
	s_lshl_b32 s17, s15, 2
	s_and_b32 s17, s17, 28
	v_sub_u32_e64 v0, s17, 1 clamp
	s_max_u32 s21, s17, 4
	v_readfirstlane_b32 s17, v0
	s_min_u32 s17, s17, 24
	s_sub_i32 s17, s17, s21
	s_lshl_b32 s17, s17, 1
	s_add_i32 s17, s17, 24
	v_writelane_b32 v253, s17, 37
	s_ashr_i32 s17, s16, 31
	s_lshl_b32 s21, s21, 6
	s_lshl_b64 s[16:17], s[16:17], 11
	s_addk_i32 s21, 0xff00
	s_add_u32 s16, s16, s21
	s_addc_u32 s17, s17, 0
	s_mul_hi_u32 s21, s16, 0x3800
	s_mulk_i32 s17, 0x3800
	s_lshl_b32 s15, s15, 4
	s_add_i32 s17, s21, s17
	s_and_b32 s15, s15, 0xffffff80
	v_writelane_b32 v253, s17, 38
	s_mulk_i32 s16, 0x3800
	s_add_i32 s98, s15, 0x300
	v_writelane_b32 v253, s16, 39
	s_lshl_b64 s[16:17], s[98:99], 1
	s_ashr_i32 s7, s7, 7
	v_writelane_b32 v253, s16, 40
	s_add_i32 s7, s7, s18
	s_nop 0
	v_writelane_b32 v253, s17, 41
	v_add_co_u32_e64 v0, s[16:17], s7, 1
	s_mulk_i32 s7, 0x300
	s_sub_i32 s7, s24, s7
	s_mul_i32 s15, s7, 0x2aab
	s_lshr_b32 s18, s15, 31
	s_ashr_i32 s15, s15, 19
	s_add_i32 s15, s15, s18
	s_mul_i32 s18, s15, 48
	s_sub_i32 s7, s7, s18
	s_sext_i32_i16 s7, s7
	s_mul_hi_i32 s18, s15, 0x1c00000
	v_writelane_b32 v253, s18, 42
	s_lshl_b32 s18, s7, 4
	s_and_b32 s18, s18, 0xffffff80
	s_mul_i32 s15, s15, 0x1c00000
	s_add_i32 s98, s18, 0xf00
	v_writelane_b32 v253, s15, 43
	s_lshl_b64 s[52:53], s[98:99], 1
	v_writelane_b32 v253, s52, 44
	s_and_b32 s15, s7, 7
	s_add_i32 s18, s24, 0x2ff
	v_writelane_b32 v253, s53, 45
	v_cmp_ne_u32_e64 s[52:53], 2, v0
	s_bfe_u32 s21, s7, 0x20001
	s_and_b32 s7, s7, 1
	v_writelane_b32 v253, s52, 46
	s_cmpk_lt_u32 s18, 0x5ff
	s_mulk_i32 s21, 0x3800
	v_writelane_b32 v253, s53, 47
	s_cselect_b32 s7, s7, s15
	v_writelane_b32 v253, s24, 48
	s_cselect_b32 s18, s21, 0
	s_lshl_b32 s7, s7, 8
	v_writelane_b32 v253, s18, 49
	s_and_b64 s[16:17], s[16:17], exec
	v_writelane_b32 v253, s7, 50
	s_cselect_b32 s7, s47, 0x200
	v_writelane_b32 v253, s7, 51
	s_cselect_b32 s16, 0x3800, s44
	s_mov_b32 s17, s99
	v_writelane_b32 v253, s16, 52
	s_mul_i32 s7, s15, 0x7000
	s_lshl_b64 s[8:9], s[8:9], 11
	v_writelane_b32 v253, s17, 53
	v_writelane_b32 v253, s7, 54
	v_writelane_b32 v253, s8, 55
	s_lshl_b32 s7, s66, 8
	s_and_b32 s7, s7, 0x700
	v_writelane_b32 v253, s9, 56
	v_writelane_b32 v253, s7, 57
	s_lshl_b32 s7, s66, 4
	s_and_b32 s7, s7, 0x180
	s_or_b32 s7, s7, 0x1800
	s_lshl_b32 s1, s1, 4
	v_writelane_b32 v253, s7, 58
	s_and_b32 s1, s1, 0xffffff80
	v_writelane_b32 v253, s28, 59
	s_addk_i32 s1, 0xc00
	v_writelane_b32 v253, s1, 60
	s_ashr_i32 s1, s0, 31
	s_lshl_b64 s[8:9], s[0:1], 11
	s_lshl_b32 s0, s14, 8
	s_and_b32 s7, s28, 0x1ffffff0
	s_add_i32 s0, s0, s31
	v_writelane_b32 v253, s0, 61
	s_and_b64 s[0:1], s[10:11], exec
	s_cselect_b32 s0, 0, 2
	v_writelane_b32 v253, s0, 62
	s_or_b32 s0, s8, s13
	s_mov_b32 s1, s9
	v_writelane_b32 v253, s0, 63
	v_sub_u32_e64 v0, s7, 8 clamp
	s_add_i32 s98, s45, 0xf00
	v_writelane_b32 v254, s1, 0
	s_lshl_b32 s0, s12, 1
	s_or_b32 s8, s8, s0
	v_writelane_b32 v254, s8, 1
	v_readfirstlane_b32 s0, v0
	s_min_u32 s18, s0, 32
	v_writelane_b32 v254, s9, 2
	v_writelane_b32 v254, s7, 3
	s_mul_hi_i32 s0, s6, 0x1c00000
	v_writelane_b32 v254, s0, 4
	s_mul_i32 s0, s6, 0x1c00000
	v_writelane_b32 v254, s0, 5
	s_lshl_b64 s[0:1], s[98:99], 1
	v_writelane_b32 v254, s0, 6
	s_add_i32 s98, s45, 0xc00
	s_ashr_i32 s47, s46, 31
	v_writelane_b32 v254, s1, 7
	s_lshl_b32 s0, s20, 8
	s_and_b32 s1, s0, 0x700
	s_max_u32 s0, s1, 64
	s_mulk_i32 s0, 0x3800
	v_writelane_b32 v254, s0, 8
	s_max_u32 s0, s1, 32
	s_mulk_i32 s0, 0x3800
	v_writelane_b32 v254, s0, 9
	v_writelane_b32 v254, s45, 10
	v_writelane_b32 v254, s1, 11
	s_add_i32 s0, s1, s31
	v_writelane_b32 v254, s0, 12
	s_lshl_b64 s[0:1], s[98:99], 1
	v_writelane_b32 v254, s0, 13
	s_ashr_i32 s81, s80, 31
	s_mov_b64 s[44:45], 0x80
	v_writelane_b32 v254, s1, 14
	s_add_i32 s0, s5, s50
	s_ashr_i32 s1, s0, 31
	s_lshr_b32 s1, s1, 26
	s_add_i32 s1, s0, s1
	s_ashr_i32 s5, s1, 6
	s_and_b32 s1, s1, 0xffc0
	s_sub_i32 s1, s0, s1
	s_bfe_i32 s0, s1, 0x80000
	s_bfe_u32 s0, s0, 0x3000c
	s_add_i32 s6, s1, s0
	s_bfe_i32 s0, s6, 0x80000
	s_and_b32 s6, s6, 0xf8
	s_sub_i32 s1, s1, s6
	s_lshl_b32 s5, s5, 3
	s_sext_i32_i16 s7, s0
	s_sext_i32_i8 s1, s1
	s_add_i32 s8, s5, s1
	s_ashr_i32 s1, s7, 3
	v_writelane_b32 v254, s1, 15
	s_mov_b32 s6, s8
	s_lshr_b32 s0, s7, 3
	s_ashr_i32 s9, s8, 31
	v_writelane_b32 v254, s6, 16
	s_bfe_i64 s[0:1], s[0:1], 0x100000
	s_lshl_b64 s[0:1], s[0:1], 20
	v_writelane_b32 v254, s7, 17
	s_lshl_b64 s[6:7], s[8:9], 20
	v_writelane_b32 v254, s6, 18
	s_nop 1
	v_writelane_b32 v254, s7, 19
	v_writelane_b32 v254, s0, 20
	s_nop 1
	v_writelane_b32 v254, s1, 21
	s_mov_b32 s0, s46
	v_writelane_b32 v254, s0, 22
	s_nop 1
	v_writelane_b32 v254, s1, 23
	s_lshl_b64 s[0:1], s[46:47], 20
	v_writelane_b32 v254, s0, 24
	s_sub_i32 s46, 0, s95
	s_mov_b32 s47, 0xc0000
	v_writelane_b32 v254, s1, 25
	s_bfe_i64 s[0:1], s[4:5], 0x100000
	s_lshl_b64 s[0:1], s[0:1], 20
	v_writelane_b32 v254, s0, 26
	s_nop 1
	v_writelane_b32 v254, s1, 27
	v_writelane_b32 v254, s29, 28
	s_or_b32 s0, s19, s29
	s_lshr_b32 s1, s34, 1
	v_writelane_b32 v254, s0, 29
	s_lshl_b32 s0, s18, 2
	s_and_b32 s1, s1, 0x7fffffc0
	s_sub_i32 s0, s0, s1
	s_bfe_u32 s1, s34, 0x10006
	s_mulk_i32 s1, 0xf8
	s_sub_i32 s0, s0, s1
	s_add_i32 s0, s0, 0
	s_add_i32 s0, s0, 0x182b0
	v_writelane_b32 v254, s0, 30
	s_sub_i32 s0, -2, s95
	v_writelane_b32 v254, s0, 31
	s_sub_i32 s0, 0, s31
	v_writelane_b32 v254, s0, 32
	s_lshl_b64 s[0:1], s[80:81], 12
	s_add_u32 s4, s0, 0x13400000
	v_writelane_b32 v254, s4, 33
	s_addc_u32 s4, s1, 0
	v_writelane_b32 v254, s4, 34
	s_ashr_i32 s49, s48, 31
	v_writelane_b32 v254, s48, 35
	s_lshl_b64 s[4:5], s[48:49], 12
	s_mov_b32 s19, 0
	v_writelane_b32 v254, s49, 36
	v_writelane_b32 v254, s4, 37
	s_nop 1
	v_writelane_b32 v254, s5, 38
	s_mov_b32 s4, s80
	v_writelane_b32 v254, s4, 39
	s_nop 1
	v_writelane_b32 v254, s5, 40
	s_lshl_b64 s[4:5], s[80:81], 13
	s_add_u32 s6, s38, s4
	v_writelane_b32 v254, s4, 41
	s_addc_u32 s7, s39, s5
	s_lshl_b64 s[78:79], s[48:49], 13
	v_writelane_b32 v254, s5, 42
	s_add_u32 s0, s0, 0x1b400000
	v_writelane_b32 v254, s0, 43
	s_addc_u32 s0, s1, 0
	v_writelane_b32 v254, s0, 44
	s_add_u32 s0, s6, 0x1000
	v_writelane_b32 v254, s6, 45
	s_addc_u32 s1, s7, 0
	v_readlane_b32 s48, v252, 0
	v_writelane_b32 v254, s7, 46
	v_writelane_b32 v254, s0, 47
	v_readlane_b32 s56, v252, 8
	v_readlane_b32 s57, v252, 9
	v_writelane_b32 v254, s1, 48
	s_add_i32 s0, 0, 0x23fc0
	v_writelane_b32 v254, s0, 49
	s_add_i32 s0, 0, 0x23fc4
	v_writelane_b32 v254, s0, 50
	s_add_i32 s0, 0, 0x18100
	v_writelane_b32 v254, s0, 51
	s_add_i32 s0, 0, 0x18900
	v_writelane_b32 v254, s0, 52
	s_mov_b64 s[0:1], s[56:57]
	v_writelane_b32 v254, s0, 53
	s_mov_b64 s[56:57], s[26:27]
	v_readlane_b32 s49, v252, 1
	v_writelane_b32 v254, s1, 54
	v_writelane_b32 v254, s72, 55
	v_readlane_b32 s50, v252, 2
	v_readlane_b32 s51, v252, 3
	v_writelane_b32 v254, s73, 56
	v_writelane_b32 v254, s74, 57
	v_readlane_b32 s52, v252, 4
	v_readlane_b32 s53, v252, 5
	v_writelane_b32 v254, s75, 58
	v_writelane_b32 v254, s76, 59
	v_readlane_b32 s54, v252, 6
	v_readlane_b32 s55, v252, 7
	v_writelane_b32 v254, s77, 60
	v_writelane_b32 v254, s90, 61
	v_readlane_b32 s58, v252, 10
	v_readlane_b32 s59, v252, 11
	v_writelane_b32 v254, s91, 62
	v_writelane_b32 v254, s56, 63
	v_readlane_b32 s60, v252, 12
	v_readlane_b32 s61, v252, 13
	v_writelane_b32 v255, s57, 0
	v_writelane_b32 v255, s96, 1
	v_readlane_b32 s62, v252, 14
	v_readlane_b32 s63, v252, 15
	v_writelane_b32 v255, s97, 2
	v_writelane_b32 v255, s68, 3
	s_nop 1
	v_writelane_b32 v255, s69, 4
	v_writelane_b32 v255, s70, 5
	v_readlane_b32 s0, v255, 1
	v_readlane_b32 s1, v255, 2
	v_mov_b32_e32 v0, 0
	s_nop 4
	global_load_dword v0, v0, s[0:1] offset:256 sc1
	s_waitcnt vmcnt(0)
	v_readfirstlane_b32 s0, v0
	s_nop 3
	v_writelane_b32 v255, s0, 12
	s_branch .LBB0_131

.LBB0_625:
	s_waitcnt vmcnt(0)
	s_waitcnt lgkmcnt(0)
	s_barrier
	s_getreg_b32 s0, hwreg(HW_REG_XCC_ID, 0, 4)
	s_waitcnt vmcnt(0)
	v_readlane_b32 s64, v252, 18
	v_readlane_b32 s65, v252, 19
	s_waitcnt vmcnt(0) lgkmcnt(0)
	s_barrier
	s_and_saveexec_b64 s[4:5], s[64:65]
	v_readlane_b32 s68, v255, 3
	v_readlane_b32 s96, v255, 1
	v_readlane_b32 s69, v255, 4
	v_readlane_b32 s72, v254, 55
	v_readlane_b32 s74, v254, 57
	v_readlane_b32 s76, v254, 59
	v_readlane_b32 s90, v254, 61
	v_readlane_b32 s56, v254, 63
	v_readlane_b32 s60, v254, 37
	v_readlane_b32 s97, v255, 2
	v_readlane_b32 s69, v252, 20
	s_movk_i32 s67, 0x1c1
	v_readlane_b32 s70, v255, 5
	v_readlane_b32 s73, v254, 56
	v_readlane_b32 s75, v254, 58
	v_readlane_b32 s77, v254, 60
	v_readlane_b32 s91, v254, 62
	v_readlane_b32 s57, v255, 0
	v_readlane_b32 s58, v254, 35
	v_readlane_b32 s61, v254, 38
	v_readlane_b32 s59, v254, 36
	s_cbranch_execz .LBB0_679
	v_readlane_b32 s1, v255, 12
	s_cmp_lg_u32 s1, 0
	s_cbranch_scc1 .Lgrp_fallback
	s_lshr_b32 s1, s66, 3
	s_lshl_b32 s1, s1, 6
	s_add_u32 s0, s96, s1
	s_addc_u32 s1, s97, 0
	s_add_u32 s0, s0, 0x1c00
	s_addc_u32 s1, s1, 0
	v_mov_b32_e32 v0, 0
	v_mov_b32_e32 v2, 1
	global_atomic_add v0, v2, s[0:1]
	s_branch .LBB0_679
.Lgrp_fallback:
	v_readlane_b32 s1, v254, 49
	s_waitcnt vmcnt(0) expcnt(0) lgkmcnt(0)
	s_and_b32 s10, s0, 15
	v_mov_b32_e32 v0, s1
	ds_read_b32 v3, v0
	v_readlane_b32 s1, v254, 50
	s_waitcnt lgkmcnt(0)
	v_cmp_ne_u32_e32 vcc, 0, v3
	v_mov_b32_e32 v0, s1
	ds_read_b32 v2, v0
	s_cbranch_vccnz .LBB0_643
	s_mov_b32 s11, 1
	s_branch .LBB0_629

.LBB0_679:
	s_or_b64 exec, exec, s[4:5]
	s_mov_b64 s[10:11], s[40:41]
	s_waitcnt lgkmcnt(0)
	s_barrier
	s_mov_b32 s101, 1
	s_add_u32 s4, s10, 0xd200000
	s_addc_u32 s5, s11, 0
	s_add_u32 s8, s10, 0x13400000
	s_addc_u32 s9, s11, 0
	s_add_u32 s12, s10, 0x1b400000
	s_addc_u32 s13, s11, 0
	v_readlane_b32 s0, v254, 5
	s_add_u32 s0, s12, s0
	v_readlane_b32 s1, v254, 4
	v_mbcnt_lo_u32_b32 v0, -1, 0
	v_mbcnt_hi_u32_b32 v0, -1, v0
	s_addc_u32 s1, s13, s1
	v_add_u32_e32 v6, s69, v0
	v_readlane_b32 s6, v254, 6
	v_readlane_b32 s7, v254, 7
	s_add_u32 s20, s0, s6
	v_bfe_u32 v0, v6, 4, 2
	v_readlane_b32 s0, v252, 52
	s_addc_u32 s21, s1, s7
	v_and_b32_e32 v3, 15, v6
	v_or_b32_e32 v2, s0, v0
	v_lshlrev_b32_e32 v0, 2, v0
	v_readlane_b32 s0, v254, 8
	v_mul_lo_u32 v2, v2, s43
	v_bitop3_b32 v0, v0, v3, s84 bitop3:0x36
	s_add_u32 s0, s20, s0
	v_lshl_or_b32 v118, v0, 4, v2
	v_mov_b32_e32 v119, v1
	s_addc_u32 s1, s21, 0
	v_lshl_add_u64 v[2:3], s[0:1], 0, v[118:119]
	s_mov_b32 s0, 0xfff20000
	s_mov_b32 s1, -1
	v_lshl_add_u64 v[4:5], v[2:3], 0, s[0:1]
	s_mov_b32 s0, 0xfff20600
	s_mov_b32 m0, s85
	s_mov_b32 s1, -1
	global_load_lds_dwordx4 v[4:5], off
	v_lshl_add_u64 v[2:3], v[2:3], 0, s[0:1]
	s_add_i32 m0, s85, 0x2000
	v_readlane_b32 s0, v254, 9
	s_add_u32 s0, s20, s0
	s_addc_u32 s1, s21, 0
	global_load_lds_dwordx4 v[2:3], off
	v_lshl_add_u64 v[2:3], s[0:1], 0, v[118:119]
	s_mov_b32 s0, 0xfff90000
	s_mov_b32 s1, -1
	v_lshl_add_u64 v[4:5], v[2:3], 0, s[0:1]
	s_mov_b32 s0, 0xfff90600
	s_add_i32 m0, s85, 0x4000
	s_mov_b32 s1, -1
	v_readlane_b32 s50, v254, 11
	global_load_lds_dwordx4 v[4:5], off
	v_lshl_add_u64 v[2:3], v[2:3], 0, s[0:1]
	s_add_i32 m0, s85, 0x6000
	s_mul_i32 s0, s50, 0x3800
	s_add_u32 s0, s20, s0
	s_addc_u32 s1, s21, 0
	global_load_lds_dwordx4 v[2:3], off
	v_lshl_add_u64 v[2:3], s[0:1], 0, v[118:119]
	s_add_i32 m0, s85, 0x8000
	v_lshl_add_u64 v[4:5], v[2:3], 0, s[92:93]
	global_load_lds_dwordx4 v118, s[0:1]
	s_add_i32 m0, s85, 0xa000
	s_mov_b64 s[0:1], 0x70000
	global_load_lds_dwordx4 v[4:5], off
	v_lshl_add_u64 v[4:5], v[2:3], 0, s[0:1]
	s_mov_b64 s[0:1], 0x70600
	v_lshl_add_u64 v[2:3], v[2:3], 0, s[0:1]
	v_and_b32_e32 v7, 31, v6
	v_readlane_b32 s0, v254, 12
	s_add_i32 m0, s85, 0xc000
	v_mov_b32_e32 v121, v1
	v_or_b32_e32 v0, s0, v7
	v_readlane_b32 s0, v253, 14
	global_load_lds_dwordx4 v[4:5], off
	s_add_i32 m0, s85, 0xe000
	v_readlane_b32 s1, v253, 15
	global_load_lds_dwordx4 v[2:3], off
	s_nop 0
	v_lshl_add_u64 v[2:3], s[0:1], 0, v[0:1]
	v_mov_b64_e32 v[4:5], s[12:13]
	v_mad_u64_u32 v[4:5], s[0:1], v2, s43, v[4:5]
	v_readlane_b32 s0, v254, 13
	v_mad_i32_i24 v5, v3, s43, v5
	v_readlane_b32 s1, v254, 14
	v_lshrrev_b32_e32 v0, 1, v6
	s_waitcnt vmcnt(4)
	v_and_b32_e32 v120, 16, v0
	v_lshl_add_u64 v[2:3], v[4:5], 0, s[0:1]
	s_waitcnt lgkmcnt(0)
	s_barrier
	v_lshl_add_u64 v[2:3], v[2:3], 0, v[120:121]
	global_load_dwordx4 v[82:85], v[2:3], off
	global_load_dwordx4 v[86:89], v[2:3], off offset:32
	global_load_dwordx4 v[90:93], v[2:3], off offset:64
	global_load_dwordx4 v[94:97], v[2:3], off offset:96
	global_load_dwordx4 v[98:101], v[2:3], off offset:128
	global_load_dwordx4 v[102:105], v[2:3], off offset:160
	global_load_dwordx4 v[106:109], v[2:3], off offset:192
	global_load_dwordx4 v[110:113], v[2:3], off offset:224
	v_readlane_b32 s0, v253, 4
	v_and_b32_e32 v0, 7, v6
	v_lshlrev_b32_e32 v122, 4, v0
	v_mov_b32_e32 v2, s0
	s_movk_i32 s0, 0x90
	v_bfe_u32 v124, v6, 3, 3
	v_mov_b32_e32 v123, v1
	v_mad_u32_u24 v129, v7, s0, v2
	v_mad_u32_u24 v131, v124, s0, v2
	v_lshl_add_u64 v[4:5], s[10:11], 0, v[122:123]
	s_mov_b64 s[0:1], 0xd400000
	v_lshl_add_u64 v[132:133], v[4:5], 0, s[0:1]
	s_mov_b64 s[0:1], 0x10400000
	v_bfe_u32 v3, v6, 5, 1
	v_lshlrev_b32_e32 v0, 3, v0
	v_lshl_add_u64 v[134:135], v[4:5], 0, s[0:1]
	v_readlane_b32 s0, v254, 32
	v_and_b32_e32 v125, 63, v6
	v_lshlrev_b32_e32 v8, 3, v3
	v_or_b32_e32 v2, 64, v0
	v_lshl_add_u32 v3, v3, 2, s0
	s_mov_b32 s19, 4
	v_or_b32_e32 v127, s31, v7
	v_cmp_gt_u32_e64 s[6:7], 32, v125
	v_or_b32_e32 v126, 8, v124
	v_or_b32_e32 v128, 16, v124
	v_or_b32_e32 v130, 24, v124
	v_add_u32_e32 v217, 0x480, v131
	v_add_u32_e32 v218, 0x900, v131
	v_add_u32_e32 v219, 0xd80, v131
	v_sub_u32_e32 v123, v3, v7
	s_mov_b32 s28, 0
	s_mov_b64 s[24:25], 0
	v_lshlrev_b32_e32 v136, 1, v0
	v_lshlrev_b32_e32 v138, 1, v2
	v_add_u32_e32 v220, v129, v8
	s_mov_b32 s51, 4
	s_mov_b32 s49, s66
	s_mov_b32 s48, 0
	s_mov_b32 s29, s66
	v_and_b32_e32 v240, 31, v125
	v_lshrrev_b32_e32 v241, 5, v125
	v_lshlrev_b32_e32 v242, 2, v125
	v_and_b32_e32 v242, 12, v242
	v_bfe_u32 v243, v125, 2, 2
	v_or_b32_e32 v242, v242, v243
	v_xor_b32_e32 v244, v241, v242
	v_lshlrev_b32_e32 v244, 4, v244
	v_lshl_add_u32 v238, v240, 8, v244
	v_lshl_or_b32 v245, v241, 2, v243
	v_lshlrev_b32_e32 v246, 2, v243
	v_or_b32_e32 v246, v246, v241
	v_bfe_u32 v247, v125, 1, 1
	v_lshrrev_b32_e32 v248, 3, v125
	v_and_or_b32 v247, v248, 2, v247
	v_xor_b32_e32 v247, v247, v246
	v_lshlrev_b32_e32 v247, 4, v247
	v_lshl_add_u32 v247, v245, 8, v247
	v_lshlrev_b32_e32 v248, 3, v125
	v_and_b32_e32 v248, 8, v248
	v_add_u32_e32 v239, v247, v248
	v_add_u32_e32 v239, 0x2000, v239
	s_waitcnt vmcnt(0)
	s_branch .LBB0_681
.LBB0_680:
	s_or_b64 exec, exec, s[0:1]
	s_cmp_eq_u32 s101, 0
	s_cbranch_scc1 .Lgw_done
	s_mov_b32 s101, 0
	v_readlane_b32 s14, v255, 12
	s_cmp_lg_u32 s14, 0
	s_cbranch_scc1 .Lgw_done
	v_readlane_b32 s100, v255, 6
	v_readlane_b32 s16, v255, 1
	v_readlane_b32 s17, v255, 2
	s_lshl_b32 s100, s100, 3
	s_add_i32 s100, s100, 8
	s_lshr_b32 s14, s66, 3
	s_lshl_b32 s14, s14, 6
	s_add_u32 s16, s16, s14
	s_addc_u32 s17, s17, 0
	s_add_u32 s16, s16, 0x1c00
	s_addc_u32 s17, s17, 0
	s_mov_b32 s15, 0
	v_mov_b32_e32 v70, 0
.Lgw_poll:
	global_load_dword v71, v70, s[16:17] sc1
	s_waitcnt vmcnt(0)
	v_readfirstlane_b32 s14, v71
	s_cmp_ge_u32 s14, s100
	s_cbranch_scc1 .Lgw_ok
	s_sleep 1
	s_add_i32 s15, s15, 1
	s_cmp_lt_u32 s15, 0x4000
	s_cbranch_scc1 .Lgw_poll
.Lgw_ok:
	buffer_inv sc1
	s_waitcnt vmcnt(0)
.Lgw_done:
	s_ashr_i32 s14, s11, 3
	s_lshl_b32 s16, s14, 7
	s_ashr_i32 s11, s10, 31
	s_ashr_i32 s15, s14, 31
	s_ashr_i32 s17, s16, 31
	s_lshl_b64 s[10:11], s[10:11], 11
	s_add_i32 s52, s52, s31
	s_add_u32 s1, s10, s52
	s_addc_u32 s0, s11, 0
	s_lshl_b64 s[86:87], s[16:17], 1
	s_add_u32 s10, s12, s86
	s_addc_u32 s11, s13, s87
	v_or_b32_e32 v196, s1, v124
	v_mov_b64_e32 v[34:35], s[10:11]
	v_mad_u64_u32 v[36:37], s[10:11], v196, s43, v[34:35]
	v_lshl_add_u64 v[42:43], v[134:135], 0, s[86:87]
	v_mad_i32_i24 v37, s0, v211, v37
	s_mov_b64 s[16:17], 0x2a00
	v_lshl_add_u64 v[142:143], v[36:37], 0, s[16:17]
	v_mov_b32_e32 v137, v1
	v_mad_u64_u32 v[146:147], s[10:11], v196, s94, v[42:43]
	s_waitcnt lgkmcnt(0)
	v_lshl_add_u64 v[38:39], v[132:133], 0, s[86:87]
	v_lshl_add_u64 v[36:37], v[142:143], 0, v[136:137]
	v_mad_i32_i24 v147, s0, v214, v147
	global_load_dwordx4 v[70:73], v[36:37], off
	global_load_dwordx4 v[78:81], v[146:147], off
	v_mad_u64_u32 v[144:145], s[10:11], v196, s94, v[38:39]
	v_mad_u64_u32 v[36:37], s[10:11], v196, 24, s[4:5]
	v_mad_i32_i24 v37, s0, 24, v37
	s_lshl_b64 s[10:11], s[14:15], 2
	v_lshl_add_u64 v[156:157], v[36:37], 0, s[10:11]
	v_add_co_u32_e32 v158, vcc, s47, v156
	global_load_dword v0, v[156:157], off
	s_nop 0
	v_addc_co_u32_e32 v159, vcc, 0, v157, vcc
	global_load_dword v200, v[158:159], off
	v_mad_i32_i24 v145, s0, v214, v145
	global_load_dwordx4 v[74:77], v[144:145], off
	v_or_b32_e32 v194, s1, v126
	v_mad_u64_u32 v[36:37], s[14:15], v194, s43, v[34:35]
	v_mad_i32_i24 v37, s0, v211, v37
	v_lshl_add_u64 v[160:161], v[36:37], 0, s[16:17]
	v_lshl_add_u64 v[36:37], v[160:161], 0, v[136:137]
	global_load_dwordx4 v[58:61], v[36:37], off
	v_mad_u64_u32 v[36:37], s[14:15], v194, 24, s[4:5]
	v_mad_i32_i24 v37, s0, 24, v37
	v_lshl_add_u64 v[166:167], v[36:37], 0, s[10:11]
	v_add_co_u32_e32 v168, vcc, s47, v166
	v_or_b32_e32 v192, s1, v128
	s_nop 0
	v_addc_co_u32_e32 v169, vcc, 0, v167, vcc
	v_mad_u64_u32 v[36:37], s[14:15], v192, s43, v[34:35]
	global_load_dword v225, v[166:167], off
	global_load_dword v226, v[168:169], off
	v_mad_i32_i24 v37, s0, v211, v37
	v_lshl_add_u64 v[170:171], v[36:37], 0, s[16:17]
	v_lshl_add_u64 v[36:37], v[170:171], 0, v[136:137]
	global_load_dwordx4 v[46:49], v[36:37], off
	v_mad_u64_u32 v[36:37], s[14:15], v192, 24, s[4:5]
	v_mad_i32_i24 v37, s0, 24, v37
	v_or_b32_e32 v190, s1, v130
	v_lshl_add_u64 v[176:177], v[36:37], 0, s[10:11]
	v_mad_u64_u32 v[114:115], s[14:15], v190, 24, s[4:5]
	v_add_co_u32_e32 v178, vcc, s47, v176
	v_mad_u64_u32 v[34:35], s[14:15], v190, s43, v[34:35]
	v_mad_i32_i24 v115, s0, 24, v115
	v_addc_co_u32_e32 v179, vcc, 0, v177, vcc
	v_mad_i32_i24 v35, s0, v211, v35
	v_lshl_add_u64 v[186:187], v[114:115], 0, s[10:11]
	v_mad_u64_u32 v[162:163], s[14:15], v194, s94, v[38:39]
	v_mad_u64_u32 v[164:165], s[14:15], v194, s94, v[42:43]
	v_mad_u64_u32 v[172:173], s[14:15], v192, s94, v[38:39]
	v_mad_u64_u32 v[174:175], s[14:15], v192, s94, v[42:43]
	v_lshl_add_u64 v[180:181], v[34:35], 0, s[16:17]
	v_mad_u64_u32 v[182:183], s[14:15], v190, s94, v[38:39]
	v_mad_u64_u32 v[184:185], s[14:15], v190, s94, v[42:43]
	v_add_co_u32_e32 v188, vcc, s47, v186
	v_mad_i32_i24 v163, s0, v214, v163
	v_mad_i32_i24 v165, s0, v214, v165
	v_mad_i32_i24 v173, s0, v214, v173
	v_mad_i32_i24 v175, s0, v214, v175
	v_lshl_add_u64 v[34:35], v[180:181], 0, v[136:137]
	v_mad_i32_i24 v183, s0, v214, v183
	v_mad_i32_i24 v185, s0, v214, v185
	v_addc_co_u32_e32 v189, vcc, 0, v187, vcc
	v_add_u32_e32 v221, v131, v122
	global_load_dwordx4 v[62:65], v[162:163], off
	global_load_dwordx4 v[66:69], v[164:165], off
	global_load_dwordx4 v[50:53], v[172:173], off
	global_load_dwordx4 v[54:57], v[174:175], off
	global_load_dword v223, v[176:177], off
	global_load_dword v224, v[178:179], off
	global_load_dwordx4 v[38:41], v[182:183], off
	global_load_dwordx4 v[42:45], v[184:185], off
	global_load_dword v139, v[186:187], off
	global_load_dword v222, v[188:189], off
	s_waitcnt vmcnt(0) lgkmcnt(0)
	v_lshlrev_b32_e32 v234, 16, v70
	global_load_dwordx4 v[34:37], v[34:35], off
	ds_read_b128 v[114:117], v221
	ds_read_b32 v198, v131 offset:128
	v_and_b32_e32 v235, 0xffff0000, v70
	v_mul_f32_e32 v70, 0xbfb8aa3b, v234
	v_exp_f32_e32 v70, v70
	s_waitcnt lgkmcnt(0)
	v_and_b32_e32 v229, 0xffff0000, v114
	v_max3_f32 v201, v198, v0, v200
	v_sub_f32_e32 v198, v198, v201
	v_sub_f32_e32 v0, v0, v201
	v_exp_f32_e32 v199, v198
	v_exp_f32_e32 v198, v0
	v_sub_f32_e32 v0, v200, v201
	v_exp_f32_e32 v0, v0
	v_add_f32_e32 v70, 1.0, v70
	v_add_f32_e32 v200, v199, v198
	v_rcp_f32_e32 v236, v70
	v_add_f32_e32 v200, v0, v200
	v_rcp_f32_e32 v200, v200
	v_mul_f32_e32 v70, 0xbfb8aa3b, v235
	v_exp_f32_e32 v70, v70
	v_lshlrev_b32_e32 v230, 16, v114
	v_mul_f32_e32 v0, v0, v200
	v_pk_mul_f32 v[202:203], v[198:199], v[200:201] op_sel_hi:[1,0]
	v_lshlrev_b32_e32 v200, 16, v117
	v_and_b32_e32 v201, 0xffff0000, v77
	v_lshlrev_b32_e32 v198, 16, v77
	v_and_b32_e32 v199, 0xffff0000, v117
	v_pk_mul_f32 v[200:201], v[202:203], v[200:201] op_sel:[1,0] op_sel_hi:[0,1]
	v_add_f32_e32 v70, 1.0, v70
	v_pk_fma_f32 v[198:199], v[202:203], v[198:199], v[200:201]
	v_lshlrev_b32_e32 v200, 16, v81
	v_and_b32_e32 v201, 0xffff0000, v81
	v_rcp_f32_e32 v237, v70
	v_lshlrev_b32_e32 v70, 16, v71
	v_pk_fma_f32 v[198:199], v[0:1], v[200:201], v[198:199] op_sel_hi:[0,1,1]
	v_lshlrev_b32_e32 v200, 16, v73
	v_and_b32_e32 v201, 0xffff0000, v73
	v_mul_f32_e32 v73, 0xbfb8aa3b, v70
	v_exp_f32_e32 v73, v73
	v_and_b32_e32 v71, 0xffff0000, v71
	v_and_b32_e32 v231, 0xffff0000, v74
	v_lshlrev_b32_e32 v228, 16, v74
	v_add_f32_e32 v73, 1.0, v73
	v_rcp_f32_e32 v114, v73
	v_mul_f32_e32 v73, 0xbfb8aa3b, v71
	v_exp_f32_e32 v73, v73
	v_pk_mul_f32 v[230:231], v[202:203], v[230:231] op_sel:[1,0] op_sel_hi:[0,1]
	v_pk_fma_f32 v[228:229], v[202:203], v[228:229], v[230:231]
	v_and_b32_e32 v231, 0xffff0000, v115
	v_add_f32_e32 v73, 1.0, v73
	v_lshlrev_b32_e32 v74, 16, v115
	v_rcp_f32_e32 v115, v73
	v_lshlrev_b32_e32 v230, 16, v75
	v_and_b32_e32 v75, 0xffff0000, v75
	v_pk_mul_f32 v[74:75], v[202:203], v[74:75] op_sel:[1,0] op_sel_hi:[0,1]
	v_lshlrev_b32_e32 v232, 16, v78
	v_and_b32_e32 v233, 0xffff0000, v78
	v_lshlrev_b32_e32 v78, 16, v79
	v_and_b32_e32 v79, 0xffff0000, v79
	v_pk_fma_f32 v[74:75], v[202:203], v[230:231], v[74:75]
	v_pk_mul_f32 v[70:71], v[114:115], v[70:71]
	v_pk_fma_f32 v[74:75], v[0:1], v[78:79], v[74:75] op_sel_hi:[0,1,1]
	v_pk_mul_f32 v[70:71], v[70:71], v[74:75]
	v_lshlrev_b32_e32 v74, 16, v76
	v_and_b32_e32 v79, 0xffff0000, v76
	v_lshlrev_b32_e32 v76, 16, v80
	v_and_b32_e32 v77, 0xffff0000, v80
	v_lshlrev_b32_e32 v80, 16, v72
	v_and_b32_e32 v81, 0xffff0000, v72
	v_mul_f32_e32 v72, 0xbfb8aa3b, v80
	v_mul_f32_e32 v73, 0xbfb8aa3b, v81
	v_exp_f32_e32 v72, v72
	v_exp_f32_e32 v73, v73
	v_lshlrev_b32_e32 v78, 16, v116
	v_and_b32_e32 v75, 0xffff0000, v116
	v_pk_mul_f32 v[78:79], v[202:203], v[78:79] op_sel:[1,0] op_sel_hi:[0,1]
	v_pk_fma_f32 v[74:75], v[202:203], v[74:75], v[78:79]
	v_pk_fma_f32 v[228:229], v[0:1], v[232:233], v[228:229] op_sel_hi:[0,1,1]
	v_add_f32_e32 v72, 1.0, v72
	v_add_f32_e32 v73, 1.0, v73
	v_pk_fma_f32 v[74:75], v[0:1], v[76:77], v[74:75] op_sel_hi:[0,1,1]
	v_mul_f32_e32 v0, 0xbfb8aa3b, v200
	v_rcp_f32_e32 v72, v72
	v_rcp_f32_e32 v73, v73
	v_exp_f32_e32 v0, v0
	v_mov_b32_e32 v197, s0
	v_pk_mul_f32 v[234:235], v[236:237], v[234:235]
	v_pk_mul_f32 v[72:73], v[72:73], v[80:81]
	v_add_f32_e32 v0, 1.0, v0
	v_pk_mul_f32 v[74:75], v[72:73], v[74:75]
	v_rcp_f32_e32 v72, v0
	v_mul_f32_e32 v0, 0xbfb8aa3b, v201
	v_exp_f32_e32 v0, v0
	v_pk_mul_f32 v[228:229], v[234:235], v[228:229]
	v_cvt_pk_bf16_f32 v74, v74, v75
	v_add_u32_e32 v78, v217, v122
	v_add_f32_e32 v0, 1.0, v0
	v_rcp_f32_e32 v73, v0
	v_lshlrev_b32_e32 v80, 16, v62
	v_mov_b32_e32 v195, s0
	v_mov_b32_e32 v193, s0
	v_pk_mul_f32 v[72:73], v[72:73], v[200:201]
	v_lshlrev_b32_e32 v200, 16, v58
	v_pk_mul_f32 v[76:77], v[72:73], v[198:199]
	v_cvt_pk_bf16_f32 v73, v70, v71
	v_lshlrev_b64 v[70:71], 12, v[196:197]
	v_lshl_add_u64 v[70:71], s[8:9], 0, v[70:71]
	v_lshl_add_u64 v[70:71], v[70:71], 0, s[86:87]
	v_cvt_pk_bf16_f32 v72, v228, v229
	v_cvt_pk_bf16_f32 v75, v76, v77
	v_lshl_add_u64 v[70:71], v[70:71], 0, v[136:137]
	global_store_dwordx4 v[70:71], v[72:75], off offset:1536
	ds_read_b128 v[114:117], v78
	ds_read_b32 v0, v217 offset:128
	v_and_b32_e32 v201, 0xffff0000, v58
	v_mul_f32_e32 v58, 0xbfb8aa3b, v200
	v_exp_f32_e32 v58, v58
	s_waitcnt lgkmcnt(0)
	v_and_b32_e32 v81, 0xffff0000, v114
	v_max3_f32 v74, v0, v225, v226
	v_sub_f32_e32 v0, v0, v74
	v_exp_f32_e32 v73, v0
	v_sub_f32_e32 v0, v225, v74
	v_exp_f32_e32 v72, v0
	v_sub_f32_e32 v0, v226, v74
	v_exp_f32_e32 v0, v0
	v_add_f32_e32 v58, 1.0, v58
	v_add_f32_e32 v74, v73, v72
	v_rcp_f32_e32 v202, v58
	v_add_f32_e32 v74, v0, v74
	v_rcp_f32_e32 v74, v74
	v_mul_f32_e32 v58, 0xbfb8aa3b, v201
	v_exp_f32_e32 v58, v58
	v_lshlrev_b32_e32 v196, 16, v114
	v_mul_f32_e32 v0, v0, v74
	v_pk_mul_f32 v[76:77], v[72:73], v[74:75] op_sel_hi:[1,0]
	v_lshlrev_b32_e32 v74, 16, v117
	v_and_b32_e32 v75, 0xffff0000, v65
	v_lshlrev_b32_e32 v72, 16, v65
	v_and_b32_e32 v73, 0xffff0000, v117
	v_pk_mul_f32 v[74:75], v[76:77], v[74:75] op_sel:[1,0] op_sel_hi:[0,1]
	v_add_f32_e32 v58, 1.0, v58
	v_pk_fma_f32 v[72:73], v[76:77], v[72:73], v[74:75]
	v_lshlrev_b32_e32 v74, 16, v69
	v_and_b32_e32 v75, 0xffff0000, v69
	v_rcp_f32_e32 v203, v58
	v_lshlrev_b32_e32 v58, 16, v59
	v_pk_fma_f32 v[72:73], v[0:1], v[74:75], v[72:73] op_sel_hi:[0,1,1]
	v_lshlrev_b32_e32 v74, 16, v61
	v_and_b32_e32 v75, 0xffff0000, v61
	v_mul_f32_e32 v61, 0xbfb8aa3b, v58
	v_exp_f32_e32 v61, v61
	v_and_b32_e32 v59, 0xffff0000, v59
	v_and_b32_e32 v197, 0xffff0000, v62
	v_pk_mul_f32 v[196:197], v[76:77], v[196:197] op_sel:[1,0] op_sel_hi:[0,1]
	v_add_f32_e32 v61, 1.0, v61
	v_rcp_f32_e32 v114, v61
	v_mul_f32_e32 v61, 0xbfb8aa3b, v59
	v_exp_f32_e32 v61, v61
	v_pk_fma_f32 v[80:81], v[76:77], v[80:81], v[196:197]
	v_and_b32_e32 v197, 0xffff0000, v115
	v_lshlrev_b32_e32 v62, 16, v115
	v_add_f32_e32 v61, 1.0, v61
	v_rcp_f32_e32 v115, v61
	v_lshlrev_b32_e32 v196, 16, v63
	v_and_b32_e32 v63, 0xffff0000, v63
	v_pk_mul_f32 v[62:63], v[76:77], v[62:63] op_sel:[1,0] op_sel_hi:[0,1]
	v_lshlrev_b32_e32 v198, 16, v66
	v_and_b32_e32 v199, 0xffff0000, v66
	v_lshlrev_b32_e32 v66, 16, v67
	v_and_b32_e32 v67, 0xffff0000, v67
	v_pk_fma_f32 v[62:63], v[76:77], v[196:197], v[62:63]
	v_pk_mul_f32 v[58:59], v[114:115], v[58:59]
	v_pk_fma_f32 v[62:63], v[0:1], v[66:67], v[62:63] op_sel_hi:[0,1,1]
	v_pk_mul_f32 v[58:59], v[58:59], v[62:63]
	v_lshlrev_b32_e32 v62, 16, v64
	v_and_b32_e32 v67, 0xffff0000, v64
	v_lshlrev_b32_e32 v64, 16, v68
	v_and_b32_e32 v65, 0xffff0000, v68
	v_lshlrev_b32_e32 v68, 16, v60
	v_and_b32_e32 v69, 0xffff0000, v60
	v_mul_f32_e32 v60, 0xbfb8aa3b, v68
	v_mul_f32_e32 v61, 0xbfb8aa3b, v69
	v_exp_f32_e32 v60, v60
	v_exp_f32_e32 v61, v61
	v_lshlrev_b32_e32 v66, 16, v116
	v_and_b32_e32 v63, 0xffff0000, v116
	v_pk_mul_f32 v[66:67], v[76:77], v[66:67] op_sel:[1,0] op_sel_hi:[0,1]
	v_pk_fma_f32 v[62:63], v[76:77], v[62:63], v[66:67]
	v_pk_fma_f32 v[80:81], v[0:1], v[198:199], v[80:81] op_sel_hi:[0,1,1]
	v_add_f32_e32 v60, 1.0, v60
	v_add_f32_e32 v61, 1.0, v61
	v_pk_fma_f32 v[62:63], v[0:1], v[64:65], v[62:63] op_sel_hi:[0,1,1]
	v_mul_f32_e32 v0, 0xbfb8aa3b, v74
	v_rcp_f32_e32 v60, v60
	v_rcp_f32_e32 v61, v61
	v_exp_f32_e32 v0, v0
	v_pk_mul_f32 v[200:201], v[202:203], v[200:201]
	v_add_u32_e32 v66, v218, v122
	v_pk_mul_f32 v[60:61], v[60:61], v[68:69]
	v_add_f32_e32 v0, 1.0, v0
	v_pk_mul_f32 v[62:63], v[60:61], v[62:63]
	v_rcp_f32_e32 v60, v0
	v_mul_f32_e32 v0, 0xbfb8aa3b, v75
	v_exp_f32_e32 v0, v0
	v_pk_mul_f32 v[80:81], v[200:201], v[80:81]
	v_cvt_pk_bf16_f32 v62, v62, v63
	v_lshlrev_b32_e32 v114, 16, v46
	v_add_f32_e32 v0, 1.0, v0
	v_rcp_f32_e32 v61, v0
	v_and_b32_e32 v115, 0xffff0000, v46
	v_mul_f32_e32 v46, 0xbfb8aa3b, v114
	v_exp_f32_e32 v46, v46
	v_pk_mul_f32 v[60:61], v[60:61], v[74:75]
	v_and_b32_e32 v77, 0xffff0000, v50
	v_pk_mul_f32 v[64:65], v[60:61], v[72:73]
	v_cvt_pk_bf16_f32 v61, v58, v59
	v_lshlrev_b64 v[58:59], 12, v[194:195]
	v_lshl_add_u64 v[58:59], s[8:9], 0, v[58:59]
	v_lshl_add_u64 v[58:59], v[58:59], 0, s[86:87]
	v_cvt_pk_bf16_f32 v60, v80, v81
	v_cvt_pk_bf16_f32 v63, v64, v65
	v_lshl_add_u64 v[58:59], v[58:59], 0, v[136:137]
	global_store_dwordx4 v[58:59], v[60:63], off offset:1536
	ds_read_b128 v[72:75], v66
	ds_read_b32 v0, v218 offset:128
	v_add_f32_e32 v46, 1.0, v46
	v_rcp_f32_e32 v116, v46
	v_mul_f32_e32 v46, 0xbfb8aa3b, v115
	v_exp_f32_e32 v46, v46
	s_waitcnt lgkmcnt(0)
	v_max3_f32 v62, v0, v223, v224
	v_sub_f32_e32 v0, v0, v62
	v_exp_f32_e32 v61, v0
	v_sub_f32_e32 v0, v223, v62
	v_exp_f32_e32 v60, v0
	v_sub_f32_e32 v0, v224, v62
	v_exp_f32_e32 v0, v0
	v_add_f32_e32 v46, 1.0, v46
	v_add_f32_e32 v62, v61, v60
	v_rcp_f32_e32 v117, v46
	v_add_f32_e32 v62, v0, v62
	v_rcp_f32_e32 v62, v62
	v_lshlrev_b32_e32 v46, 16, v47
	v_and_b32_e32 v47, 0xffff0000, v47
	v_and_b32_e32 v69, 0xffff0000, v72
	v_mul_f32_e32 v0, v0, v62
	v_pk_mul_f32 v[64:65], v[60:61], v[62:63] op_sel_hi:[1,0]
	v_lshlrev_b32_e32 v62, 16, v75
	v_and_b32_e32 v63, 0xffff0000, v53
	v_lshlrev_b32_e32 v60, 16, v53
	v_and_b32_e32 v61, 0xffff0000, v75
	v_pk_mul_f32 v[62:63], v[64:65], v[62:63] op_sel:[1,0] op_sel_hi:[0,1]
	v_pk_fma_f32 v[60:61], v[64:65], v[60:61], v[62:63]
	v_lshlrev_b32_e32 v62, 16, v57
	v_and_b32_e32 v63, 0xffff0000, v57
	v_pk_fma_f32 v[60:61], v[0:1], v[62:63], v[60:61] op_sel_hi:[0,1,1]
	v_lshlrev_b32_e32 v62, 16, v49
	v_and_b32_e32 v63, 0xffff0000, v49
	v_mul_f32_e32 v49, 0xbfb8aa3b, v46
	v_exp_f32_e32 v49, v49
	v_lshlrev_b32_e32 v76, 16, v72
	v_lshlrev_b32_e32 v68, 16, v50
	v_pk_mul_f32 v[76:77], v[64:65], v[76:77] op_sel:[1,0] op_sel_hi:[0,1]
	v_add_f32_e32 v49, 1.0, v49
	v_rcp_f32_e32 v72, v49
	v_mul_f32_e32 v49, 0xbfb8aa3b, v47
	v_exp_f32_e32 v49, v49
	v_pk_fma_f32 v[68:69], v[64:65], v[68:69], v[76:77]
	v_and_b32_e32 v77, 0xffff0000, v73
	v_lshlrev_b32_e32 v50, 16, v73
	v_add_f32_e32 v49, 1.0, v49
	v_rcp_f32_e32 v73, v49
	v_lshlrev_b32_e32 v76, 16, v51
	v_and_b32_e32 v51, 0xffff0000, v51
	v_pk_mul_f32 v[50:51], v[64:65], v[50:51] op_sel:[1,0] op_sel_hi:[0,1]
	v_lshlrev_b32_e32 v80, 16, v54
	v_and_b32_e32 v81, 0xffff0000, v54
	v_lshlrev_b32_e32 v54, 16, v55
	v_and_b32_e32 v55, 0xffff0000, v55
	v_pk_fma_f32 v[50:51], v[64:65], v[76:77], v[50:51]
	v_pk_mul_f32 v[46:47], v[72:73], v[46:47]
	v_pk_fma_f32 v[50:51], v[0:1], v[54:55], v[50:51] op_sel_hi:[0,1,1]
	v_pk_mul_f32 v[50:51], v[46:47], v[50:51]
	v_lshlrev_b32_e32 v46, 16, v52
	v_and_b32_e32 v55, 0xffff0000, v52
	v_lshlrev_b32_e32 v52, 16, v56
	v_and_b32_e32 v53, 0xffff0000, v56
	v_lshlrev_b32_e32 v56, 16, v48
	v_and_b32_e32 v57, 0xffff0000, v48
	v_mul_f32_e32 v48, 0xbfb8aa3b, v56
	v_mul_f32_e32 v49, 0xbfb8aa3b, v57
	v_exp_f32_e32 v48, v48
	v_exp_f32_e32 v49, v49
	v_lshlrev_b32_e32 v54, 16, v74
	v_and_b32_e32 v47, 0xffff0000, v74
	v_pk_mul_f32 v[54:55], v[64:65], v[54:55] op_sel:[1,0] op_sel_hi:[0,1]
	v_pk_fma_f32 v[46:47], v[64:65], v[46:47], v[54:55]
	v_pk_fma_f32 v[68:69], v[0:1], v[80:81], v[68:69] op_sel_hi:[0,1,1]
	v_add_f32_e32 v48, 1.0, v48
	v_add_f32_e32 v49, 1.0, v49
	v_pk_fma_f32 v[46:47], v[0:1], v[52:53], v[46:47] op_sel_hi:[0,1,1]
	v_mul_f32_e32 v0, 0xbfb8aa3b, v62
	v_rcp_f32_e32 v48, v48
	v_rcp_f32_e32 v49, v49
	v_exp_f32_e32 v0, v0
	v_pk_mul_f32 v[114:115], v[116:117], v[114:115]
	v_add_u32_e32 v67, v219, v122
	v_pk_mul_f32 v[48:49], v[48:49], v[56:57]
	v_add_f32_e32 v0, 1.0, v0
	v_pk_mul_f32 v[48:49], v[48:49], v[46:47]
	v_rcp_f32_e32 v46, v0
	v_mul_f32_e32 v0, 0xbfb8aa3b, v63
	v_exp_f32_e32 v0, v0
	v_pk_mul_f32 v[68:69], v[114:115], v[68:69]
	v_cvt_pk_bf16_f32 v48, v48, v49
	v_and_b32_e32 v57, 0xffff0000, v38
	v_add_f32_e32 v0, 1.0, v0
	v_rcp_f32_e32 v47, v0
	v_lshlrev_b32_e32 v64, 16, v42
	v_and_b32_e32 v65, 0xffff0000, v42
	v_lshlrev_b32_e32 v42, 16, v43
	v_pk_mul_f32 v[46:47], v[46:47], v[62:63]
	v_and_b32_e32 v43, 0xffff0000, v43
	v_pk_mul_f32 v[52:53], v[46:47], v[60:61]
	v_cvt_pk_bf16_f32 v47, v50, v51
	v_lshlrev_b64 v[50:51], 12, v[192:193]
	v_lshl_add_u64 v[50:51], s[8:9], 0, v[50:51]
	v_lshl_add_u64 v[50:51], v[50:51], 0, s[86:87]
	v_cvt_pk_bf16_f32 v46, v68, v69
	v_cvt_pk_bf16_f32 v49, v52, v53
	v_lshl_add_u64 v[54:55], v[50:51], 0, v[136:137]
	global_store_dwordx4 v[54:55], v[46:49], off offset:1536
	ds_read_b128 v[60:63], v67
	ds_read_b32 v0, v219 offset:128
	s_waitcnt vmcnt(0)
	v_lshlrev_b32_e32 v68, 16, v34
	v_and_b32_e32 v69, 0xffff0000, v34
	v_mul_f32_e32 v34, 0xbfb8aa3b, v68
	v_exp_f32_e32 v34, v34
	s_waitcnt lgkmcnt(0)
	v_max3_f32 v48, v0, v139, v222
	v_sub_f32_e32 v0, v0, v48
	v_exp_f32_e32 v47, v0
	v_sub_f32_e32 v0, v139, v48
	v_exp_f32_e32 v46, v0
	v_sub_f32_e32 v0, v222, v48
	v_exp_f32_e32 v0, v0
	v_add_f32_e32 v34, 1.0, v34
	v_add_f32_e32 v48, v47, v46
	v_rcp_f32_e32 v72, v34
	v_add_f32_e32 v48, v0, v48
	v_rcp_f32_e32 v48, v48
	v_mul_f32_e32 v34, 0xbfb8aa3b, v69
	v_exp_f32_e32 v34, v34
	v_and_b32_e32 v53, 0xffff0000, v60
	v_mul_f32_e32 v0, v0, v48
	v_pk_mul_f32 v[50:51], v[46:47], v[48:49] op_sel_hi:[1,0]
	v_lshlrev_b32_e32 v48, 16, v63
	v_and_b32_e32 v49, 0xffff0000, v41
	v_lshlrev_b32_e32 v46, 16, v41
	v_and_b32_e32 v47, 0xffff0000, v63
	v_pk_mul_f32 v[48:49], v[50:51], v[48:49] op_sel:[1,0] op_sel_hi:[0,1]
	v_add_f32_e32 v34, 1.0, v34
	v_pk_fma_f32 v[46:47], v[50:51], v[46:47], v[48:49]
	v_lshlrev_b32_e32 v48, 16, v45
	v_and_b32_e32 v49, 0xffff0000, v45
	v_rcp_f32_e32 v73, v34
	v_lshlrev_b32_e32 v34, 16, v35
	v_pk_fma_f32 v[46:47], v[0:1], v[48:49], v[46:47] op_sel_hi:[0,1,1]
	v_lshlrev_b32_e32 v48, 16, v37
	v_and_b32_e32 v49, 0xffff0000, v37
	v_mul_f32_e32 v37, 0xbfb8aa3b, v34
	v_exp_f32_e32 v37, v37
	v_and_b32_e32 v35, 0xffff0000, v35
	v_lshlrev_b32_e32 v56, 16, v60
	v_lshlrev_b32_e32 v52, 16, v38
	v_add_f32_e32 v37, 1.0, v37
	v_rcp_f32_e32 v60, v37
	v_mul_f32_e32 v37, 0xbfb8aa3b, v35
	v_exp_f32_e32 v37, v37
	v_pk_mul_f32 v[56:57], v[50:51], v[56:57] op_sel:[1,0] op_sel_hi:[0,1]
	v_pk_fma_f32 v[52:53], v[50:51], v[52:53], v[56:57]
	v_and_b32_e32 v57, 0xffff0000, v61
	v_add_f32_e32 v37, 1.0, v37
	v_lshlrev_b32_e32 v38, 16, v61
	v_rcp_f32_e32 v61, v37
	v_lshlrev_b32_e32 v56, 16, v39
	v_and_b32_e32 v39, 0xffff0000, v39
	v_pk_mul_f32 v[38:39], v[50:51], v[38:39] op_sel:[1,0] op_sel_hi:[0,1]
	v_pk_fma_f32 v[38:39], v[50:51], v[56:57], v[38:39]
	v_pk_mul_f32 v[34:35], v[60:61], v[34:35]
	v_pk_fma_f32 v[38:39], v[0:1], v[42:43], v[38:39] op_sel_hi:[0,1,1]
	v_pk_mul_f32 v[38:39], v[34:35], v[38:39]
	v_lshlrev_b32_e32 v34, 16, v40
	v_and_b32_e32 v43, 0xffff0000, v40
	v_lshlrev_b32_e32 v40, 16, v44
	v_and_b32_e32 v41, 0xffff0000, v44
	v_lshlrev_b32_e32 v44, 16, v36
	v_and_b32_e32 v45, 0xffff0000, v36
	v_mul_f32_e32 v36, 0xbfb8aa3b, v44
	v_mul_f32_e32 v37, 0xbfb8aa3b, v45
	v_exp_f32_e32 v36, v36
	v_exp_f32_e32 v37, v37
	v_lshlrev_b32_e32 v42, 16, v62
	v_and_b32_e32 v35, 0xffff0000, v62
	v_pk_mul_f32 v[42:43], v[50:51], v[42:43] op_sel:[1,0] op_sel_hi:[0,1]
	v_pk_fma_f32 v[34:35], v[50:51], v[34:35], v[42:43]
	v_pk_fma_f32 v[52:53], v[0:1], v[64:65], v[52:53] op_sel_hi:[0,1,1]
	v_add_f32_e32 v36, 1.0, v36
	v_add_f32_e32 v37, 1.0, v37
	v_pk_fma_f32 v[34:35], v[0:1], v[40:41], v[34:35] op_sel_hi:[0,1,1]
	v_mul_f32_e32 v0, 0xbfb8aa3b, v48
	v_rcp_f32_e32 v36, v36
	v_rcp_f32_e32 v37, v37
	v_exp_f32_e32 v0, v0
	v_mov_b32_e32 v191, s0
	v_mov_b32_e32 v141, v140
	v_pk_mul_f32 v[36:37], v[36:37], v[44:45]
	v_add_f32_e32 v0, 1.0, v0
	v_pk_mul_f32 v[36:37], v[36:37], v[34:35]
	v_rcp_f32_e32 v34, v0
	v_mul_f32_e32 v0, 0xbfb8aa3b, v49
	v_exp_f32_e32 v0, v0
	v_pk_mul_f32 v[68:69], v[72:73], v[68:69]
	v_pk_mul_f32 v[18:19], v[18:19], v[140:141]
	v_pk_mul_f32 v[20:21], v[20:21], v[140:141]
	v_add_f32_e32 v0, 1.0, v0
	v_rcp_f32_e32 v35, v0
	v_pk_mul_f32 v[2:3], v[2:3], v[140:141]
	v_pk_mul_f32 v[4:5], v[4:5], v[140:141]
	v_pk_mul_f32 v[52:53], v[68:69], v[52:53]
	v_pk_mul_f32 v[34:35], v[34:35], v[48:49]
	v_cvt_pk_bf16_f32 v18, v18, v19
	v_pk_mul_f32 v[40:41], v[34:35], v[46:47]
	v_cvt_pk_bf16_f32 v35, v38, v39
	v_lshlrev_b64 v[38:39], 12, v[190:191]
	v_lshl_add_u64 v[38:39], s[8:9], 0, v[38:39]
	v_lshl_add_u64 v[38:39], v[38:39], 0, s[86:87]
	v_cvt_pk_bf16_f32 v19, v20, v21
	v_pk_mul_f32 v[20:21], v[22:23], v[140:141]
	v_pk_mul_f32 v[22:23], v[24:25], v[140:141]
	v_cvt_pk_bf16_f32 v2, v2, v3
	v_cvt_pk_bf16_f32 v3, v4, v5
	v_pk_mul_f32 v[4:5], v[6:7], v[140:141]
	v_pk_mul_f32 v[6:7], v[8:9], v[140:141]
	v_cvt_pk_bf16_f32 v34, v52, v53
	v_cvt_pk_bf16_f32 v36, v36, v37
	v_cvt_pk_bf16_f32 v37, v40, v41
	v_lshl_add_u64 v[56:57], v[38:39], 0, v[136:137]
	v_cvt_pk_bf16_f32 v20, v20, v21
	v_cvt_pk_bf16_f32 v21, v22, v23
	v_cvt_pk_bf16_f32 v4, v4, v5
	v_cvt_pk_bf16_f32 v5, v6, v7
	global_store_dwordx4 v[56:57], v[34:37], off offset:1536
	ds_write2_b64 v220, v[18:19], v[20:21] offset1:2
	v_pk_mul_f32 v[18:19], v[26:27], v[140:141]
	v_pk_mul_f32 v[20:21], v[28:29], v[140:141]
	ds_write2_b64 v220, v[2:3], v[4:5] offset0:8 offset1:10
	v_pk_mul_f32 v[2:3], v[10:11], v[140:141]
	v_pk_mul_f32 v[4:5], v[12:13], v[140:141]
	v_cvt_pk_bf16_f32 v18, v18, v19
	v_cvt_pk_bf16_f32 v19, v20, v21
	v_pk_mul_f32 v[20:21], v[30:31], v[140:141]
	v_pk_mul_f32 v[22:23], v[32:33], v[140:141]
	v_cvt_pk_bf16_f32 v2, v2, v3
	v_cvt_pk_bf16_f32 v3, v4, v5
	v_pk_mul_f32 v[4:5], v[14:15], v[140:141]
	v_pk_mul_f32 v[6:7], v[16:17], v[140:141]
	v_cvt_pk_bf16_f32 v20, v20, v21
	v_cvt_pk_bf16_f32 v21, v22, v23
	v_cvt_pk_bf16_f32 v4, v4, v5
	v_cvt_pk_bf16_f32 v5, v6, v7
	ds_write2_b64 v220, v[18:19], v[20:21] offset0:4 offset1:6
	ds_write2_b64 v220, v[2:3], v[4:5] offset0:12 offset1:14
	v_mov_b32_e32 v139, v1
	s_waitcnt lgkmcnt(0)
	v_lshl_add_u64 v[2:3], v[142:143], 0, v[138:139]
	global_load_dwordx4 v[38:41], v[2:3], off
	global_load_dwordx4 v[46:49], v[144:145], off offset:128
	global_load_dwordx4 v[42:45], v[146:147], off offset:128
	global_load_dword v0, v[156:157], off
	global_load_dword v62, v[158:159], off
	v_lshl_add_u64 v[2:3], v[160:161], 0, v[138:139]
	global_load_dwordx4 v[26:29], v[2:3], off
	global_load_dwordx4 v[34:37], v[162:163], off offset:128
	global_load_dwordx4 v[30:33], v[164:165], off offset:128
	global_load_dword v79, v[166:167], off
	global_load_dword v137, v[168:169], off
	v_lshl_add_u64 v[2:3], v[170:171], 0, v[138:139]
	global_load_dwordx4 v[14:17], v[2:3], off
	global_load_dwordx4 v[22:25], v[172:173], off offset:128
	global_load_dwordx4 v[18:21], v[174:175], off offset:128
	global_load_dword v73, v[176:177], off
	global_load_dword v72, v[178:179], off
	v_lshl_add_u64 v[2:3], v[180:181], 0, v[138:139]
	global_load_dwordx4 v[2:5], v[2:3], off
	s_nop 0
	global_load_dwordx4 v[10:13], v[182:183], off offset:128
	global_load_dwordx4 v[6:9], v[184:185], off offset:128
	global_load_dword v69, v[186:187], off
	global_load_dword v68, v[188:189], off
	ds_read_b128 v[50:53], v221
	ds_read_b32 v60, v131 offset:128
	s_andn2_b64 vcc, exec, s[26:27]
	s_waitcnt lgkmcnt(0)
	v_and_b32_e32 v75, 0xffff0000, v50
	v_lshlrev_b32_e32 v76, 16, v50
	s_waitcnt vmcnt(0)
	v_lshlrev_b32_e32 v114, 16, v38
	v_and_b32_e32 v115, 0xffff0000, v38
	v_mul_f32_e32 v38, 0xbfb8aa3b, v114
	v_exp_f32_e32 v38, v38
	v_max3_f32 v63, v60, v0, v62
	v_sub_f32_e32 v60, v60, v63
	v_sub_f32_e32 v0, v0, v63
	v_exp_f32_e32 v61, v60
	v_exp_f32_e32 v60, v0
	v_sub_f32_e32 v0, v62, v63
	v_exp_f32_e32 v0, v0
	v_add_f32_e32 v38, 1.0, v38
	v_add_f32_e32 v62, v61, v60
	v_rcp_f32_e32 v116, v38
	v_add_f32_e32 v62, v0, v62
	v_rcp_f32_e32 v62, v62
	v_mul_f32_e32 v38, 0xbfb8aa3b, v115
	v_exp_f32_e32 v38, v38
	v_and_b32_e32 v77, 0xffff0000, v46
	v_mul_f32_e32 v0, v0, v62
	v_pk_mul_f32 v[64:65], v[60:61], v[62:63] op_sel_hi:[1,0]
	v_lshlrev_b32_e32 v62, 16, v53
	v_and_b32_e32 v63, 0xffff0000, v49
	v_lshlrev_b32_e32 v60, 16, v49
	v_and_b32_e32 v61, 0xffff0000, v53
	v_pk_mul_f32 v[62:63], v[64:65], v[62:63] op_sel:[1,0] op_sel_hi:[0,1]
	v_add_f32_e32 v38, 1.0, v38
	v_pk_fma_f32 v[60:61], v[64:65], v[60:61], v[62:63]
	v_lshlrev_b32_e32 v62, 16, v45
	v_and_b32_e32 v63, 0xffff0000, v45
	v_rcp_f32_e32 v117, v38
	v_lshlrev_b32_e32 v38, 16, v39
	v_pk_fma_f32 v[60:61], v[0:1], v[62:63], v[60:61] op_sel_hi:[0,1,1]
	v_lshlrev_b32_e32 v62, 16, v41
	v_and_b32_e32 v63, 0xffff0000, v41
	v_mul_f32_e32 v41, 0xbfb8aa3b, v38
	v_exp_f32_e32 v41, v41
	v_and_b32_e32 v39, 0xffff0000, v39
	v_lshlrev_b32_e32 v74, 16, v46
	v_pk_mul_f32 v[76:77], v[64:65], v[76:77] op_sel:[1,0] op_sel_hi:[0,1]
	v_add_f32_e32 v41, 1.0, v41
	v_rcp_f32_e32 v50, v41
	v_mul_f32_e32 v41, 0xbfb8aa3b, v39
	v_exp_f32_e32 v41, v41
	v_pk_fma_f32 v[74:75], v[64:65], v[74:75], v[76:77]
	v_and_b32_e32 v77, 0xffff0000, v51
	v_lshlrev_b32_e32 v46, 16, v51
	v_add_f32_e32 v41, 1.0, v41
	v_rcp_f32_e32 v51, v41
	v_lshlrev_b32_e32 v76, 16, v47
	v_and_b32_e32 v47, 0xffff0000, v47
	v_pk_mul_f32 v[46:47], v[64:65], v[46:47] op_sel:[1,0] op_sel_hi:[0,1]
	v_lshlrev_b32_e32 v80, 16, v42
	v_and_b32_e32 v81, 0xffff0000, v42
	v_lshlrev_b32_e32 v42, 16, v43
	v_and_b32_e32 v43, 0xffff0000, v43
	v_pk_fma_f32 v[46:47], v[64:65], v[76:77], v[46:47]
	v_pk_mul_f32 v[38:39], v[50:51], v[38:39]
	v_pk_fma_f32 v[42:43], v[0:1], v[42:43], v[46:47] op_sel_hi:[0,1,1]
	v_pk_mul_f32 v[42:43], v[38:39], v[42:43]
	v_lshlrev_b32_e32 v38, 16, v48
	v_and_b32_e32 v47, 0xffff0000, v48
	v_lshlrev_b32_e32 v48, 16, v44
	v_and_b32_e32 v49, 0xffff0000, v44
	v_lshlrev_b32_e32 v44, 16, v40
	v_and_b32_e32 v45, 0xffff0000, v40
	v_mul_f32_e32 v40, 0xbfb8aa3b, v44
	v_mul_f32_e32 v41, 0xbfb8aa3b, v45
	v_exp_f32_e32 v40, v40
	v_exp_f32_e32 v41, v41
	v_lshlrev_b32_e32 v46, 16, v52
	v_and_b32_e32 v39, 0xffff0000, v52
	v_add_f32_e32 v40, 1.0, v40
	v_add_f32_e32 v41, 1.0, v41
	v_rcp_f32_e32 v40, v40
	v_rcp_f32_e32 v41, v41
	v_pk_fma_f32 v[74:75], v[0:1], v[80:81], v[74:75] op_sel_hi:[0,1,1]
	v_pk_mul_f32 v[114:115], v[116:117], v[114:115]
	v_and_b32_e32 v51, 0xffff0000, v34
	v_pk_mul_f32 v[40:41], v[40:41], v[44:45]
	v_pk_mul_f32 v[44:45], v[64:65], v[46:47] op_sel:[1,0] op_sel_hi:[0,1]
	v_pk_fma_f32 v[38:39], v[64:65], v[38:39], v[44:45]
	v_pk_mul_f32 v[74:75], v[114:115], v[74:75]
	v_pk_fma_f32 v[38:39], v[0:1], v[48:49], v[38:39] op_sel_hi:[0,1,1]
	v_mul_f32_e32 v0, 0xbfb8aa3b, v62
	v_exp_f32_e32 v0, v0
	v_pk_mul_f32 v[40:41], v[40:41], v[38:39]
	v_lshlrev_b32_e32 v48, 16, v34
	v_cvt_pk_bf16_f32 v40, v40, v41
	v_add_f32_e32 v0, 1.0, v0
	v_rcp_f32_e32 v38, v0
	v_mul_f32_e32 v0, 0xbfb8aa3b, v63
	v_exp_f32_e32 v0, v0
	v_lshlrev_b32_e32 v52, 16, v30
	v_and_b32_e32 v53, 0xffff0000, v30
	v_lshlrev_b32_e32 v30, 16, v31
	v_add_f32_e32 v0, 1.0, v0
	v_rcp_f32_e32 v39, v0
	v_and_b32_e32 v31, 0xffff0000, v31
	v_pk_mul_f32 v[38:39], v[38:39], v[62:63]
	s_nop 0
	v_pk_mul_f32 v[44:45], v[38:39], v[60:61]
	v_cvt_pk_bf16_f32 v38, v74, v75
	v_cvt_pk_bf16_f32 v39, v42, v43
	v_cvt_pk_bf16_f32 v41, v44, v45
	global_store_dwordx4 v[70:71], v[38:41], off offset:1664
	ds_read_b128 v[44:47], v78
	ds_read_b32 v0, v217 offset:128
	v_lshlrev_b32_e32 v60, 16, v26
	v_and_b32_e32 v61, 0xffff0000, v26
	v_mul_f32_e32 v26, 0xbfb8aa3b, v60
	v_exp_f32_e32 v26, v26
	s_waitcnt lgkmcnt(0)
	v_max3_f32 v40, v0, v79, v137
	v_sub_f32_e32 v0, v0, v40
	v_exp_f32_e32 v39, v0
	v_sub_f32_e32 v0, v79, v40
	v_exp_f32_e32 v38, v0
	v_sub_f32_e32 v0, v137, v40
	v_exp_f32_e32 v0, v0
	v_add_f32_e32 v26, 1.0, v26
	v_add_f32_e32 v40, v39, v38
	v_rcp_f32_e32 v62, v26
	v_add_f32_e32 v40, v0, v40
	v_rcp_f32_e32 v40, v40
	v_mul_f32_e32 v26, 0xbfb8aa3b, v61
	v_exp_f32_e32 v26, v26
	v_and_b32_e32 v49, 0xffff0000, v44
	v_mul_f32_e32 v0, v0, v40
	v_pk_mul_f32 v[42:43], v[38:39], v[40:41] op_sel_hi:[1,0]
	v_lshlrev_b32_e32 v40, 16, v47
	v_and_b32_e32 v41, 0xffff0000, v37
	v_lshlrev_b32_e32 v38, 16, v37
	v_and_b32_e32 v39, 0xffff0000, v47
	v_pk_mul_f32 v[40:41], v[42:43], v[40:41] op_sel:[1,0] op_sel_hi:[0,1]
	v_add_f32_e32 v26, 1.0, v26
	v_pk_fma_f32 v[38:39], v[42:43], v[38:39], v[40:41]
	v_lshlrev_b32_e32 v40, 16, v33
	v_and_b32_e32 v41, 0xffff0000, v33
	v_rcp_f32_e32 v63, v26
	v_lshlrev_b32_e32 v26, 16, v27
	v_pk_fma_f32 v[38:39], v[0:1], v[40:41], v[38:39] op_sel_hi:[0,1,1]
	v_lshlrev_b32_e32 v40, 16, v29
	v_and_b32_e32 v41, 0xffff0000, v29
	v_mul_f32_e32 v29, 0xbfb8aa3b, v26
	v_exp_f32_e32 v29, v29
	v_and_b32_e32 v27, 0xffff0000, v27
	v_lshlrev_b32_e32 v50, 16, v44
	v_pk_mul_f32 v[50:51], v[42:43], v[50:51] op_sel:[1,0] op_sel_hi:[0,1]
	v_add_f32_e32 v29, 1.0, v29
	v_rcp_f32_e32 v44, v29
	v_mul_f32_e32 v29, 0xbfb8aa3b, v27
	v_exp_f32_e32 v29, v29
	v_pk_fma_f32 v[48:49], v[42:43], v[48:49], v[50:51]
	v_and_b32_e32 v51, 0xffff0000, v45
	v_lshlrev_b32_e32 v34, 16, v45
	v_add_f32_e32 v29, 1.0, v29
	v_rcp_f32_e32 v45, v29
	v_lshlrev_b32_e32 v50, 16, v35
	v_and_b32_e32 v35, 0xffff0000, v35
	v_pk_mul_f32 v[34:35], v[42:43], v[34:35] op_sel:[1,0] op_sel_hi:[0,1]
	v_pk_fma_f32 v[34:35], v[42:43], v[50:51], v[34:35]
	v_pk_mul_f32 v[26:27], v[44:45], v[26:27]
	v_pk_fma_f32 v[30:31], v[0:1], v[30:31], v[34:35] op_sel_hi:[0,1,1]
	v_pk_mul_f32 v[30:31], v[26:27], v[30:31]
	v_lshlrev_b32_e32 v26, 16, v36
	v_and_b32_e32 v35, 0xffff0000, v36
	v_lshlrev_b32_e32 v36, 16, v32
	v_and_b32_e32 v37, 0xffff0000, v32
	v_lshlrev_b32_e32 v32, 16, v28
	v_and_b32_e32 v33, 0xffff0000, v28
	v_mul_f32_e32 v28, 0xbfb8aa3b, v32
	v_mul_f32_e32 v29, 0xbfb8aa3b, v33
	v_exp_f32_e32 v28, v28
	v_exp_f32_e32 v29, v29
	v_lshlrev_b32_e32 v34, 16, v46
	v_and_b32_e32 v27, 0xffff0000, v46
	v_add_f32_e32 v28, 1.0, v28
	v_add_f32_e32 v29, 1.0, v29
	v_rcp_f32_e32 v28, v28
	v_rcp_f32_e32 v29, v29
	v_pk_fma_f32 v[48:49], v[0:1], v[52:53], v[48:49] op_sel_hi:[0,1,1]
	v_pk_mul_f32 v[60:61], v[62:63], v[60:61]
	v_pk_mul_f32 v[28:29], v[28:29], v[32:33]
	v_pk_mul_f32 v[32:33], v[42:43], v[34:35] op_sel:[1,0] op_sel_hi:[0,1]
	v_pk_fma_f32 v[26:27], v[42:43], v[26:27], v[32:33]
	v_pk_mul_f32 v[48:49], v[60:61], v[48:49]
	v_pk_fma_f32 v[26:27], v[0:1], v[36:37], v[26:27] op_sel_hi:[0,1,1]
	v_mul_f32_e32 v0, 0xbfb8aa3b, v40
	v_exp_f32_e32 v0, v0
	v_pk_mul_f32 v[28:29], v[28:29], v[26:27]
	v_lshlrev_b32_e32 v42, 16, v14
	v_cvt_pk_bf16_f32 v28, v28, v29
	v_add_f32_e32 v0, 1.0, v0
	v_rcp_f32_e32 v26, v0
	v_mul_f32_e32 v0, 0xbfb8aa3b, v41
	v_exp_f32_e32 v0, v0
	v_and_b32_e32 v43, 0xffff0000, v14
	v_mul_f32_e32 v14, 0xbfb8aa3b, v42
	v_exp_f32_e32 v14, v14
	v_add_f32_e32 v0, 1.0, v0
	v_rcp_f32_e32 v27, v0
	v_lshlrev_b32_e32 v36, 16, v22
	v_add_f32_e32 v14, 1.0, v14
	v_rcp_f32_e32 v44, v14
	v_pk_mul_f32 v[26:27], v[26:27], v[40:41]
	v_mul_f32_e32 v14, 0xbfb8aa3b, v43
	v_pk_mul_f32 v[32:33], v[26:27], v[38:39]
	v_cvt_pk_bf16_f32 v26, v48, v49
	v_cvt_pk_bf16_f32 v27, v30, v31
	v_cvt_pk_bf16_f32 v29, v32, v33
	global_store_dwordx4 v[58:59], v[26:29], off offset:1664
	ds_read_b128 v[32:35], v66
	ds_read_b32 v0, v218 offset:128
	v_exp_f32_e32 v14, v14
	v_and_b32_e32 v39, 0xffff0000, v22
	v_lshlrev_b32_e32 v40, 16, v18
	s_waitcnt lgkmcnt(0)
	v_and_b32_e32 v37, 0xffff0000, v32
	v_max3_f32 v28, v0, v73, v72
	v_sub_f32_e32 v0, v0, v28
	v_exp_f32_e32 v27, v0
	v_sub_f32_e32 v0, v73, v28
	v_exp_f32_e32 v26, v0
	v_sub_f32_e32 v0, v72, v28
	v_exp_f32_e32 v0, v0
	v_add_f32_e32 v14, 1.0, v14
	v_add_f32_e32 v28, v27, v26
	v_rcp_f32_e32 v45, v14
	v_add_f32_e32 v28, v0, v28
	v_rcp_f32_e32 v28, v28
	v_lshlrev_b32_e32 v14, 16, v15
	v_and_b32_e32 v15, 0xffff0000, v15
	v_lshlrev_b32_e32 v38, 16, v32
	v_mul_f32_e32 v0, v0, v28
	v_pk_mul_f32 v[30:31], v[26:27], v[28:29] op_sel_hi:[1,0]
	v_lshlrev_b32_e32 v28, 16, v35
	v_and_b32_e32 v29, 0xffff0000, v25
	v_lshlrev_b32_e32 v26, 16, v25
	v_and_b32_e32 v27, 0xffff0000, v35
	v_pk_mul_f32 v[28:29], v[30:31], v[28:29] op_sel:[1,0] op_sel_hi:[0,1]
	v_pk_fma_f32 v[26:27], v[30:31], v[26:27], v[28:29]
	v_lshlrev_b32_e32 v28, 16, v21
	v_and_b32_e32 v29, 0xffff0000, v21
	v_pk_fma_f32 v[26:27], v[0:1], v[28:29], v[26:27] op_sel_hi:[0,1,1]
	v_lshlrev_b32_e32 v28, 16, v17
	v_and_b32_e32 v29, 0xffff0000, v17
	v_mul_f32_e32 v17, 0xbfb8aa3b, v14
	v_exp_f32_e32 v17, v17
	v_pk_mul_f32 v[38:39], v[30:31], v[38:39] op_sel:[1,0] op_sel_hi:[0,1]
	v_pk_fma_f32 v[36:37], v[30:31], v[36:37], v[38:39]
	v_and_b32_e32 v39, 0xffff0000, v33
	v_add_f32_e32 v17, 1.0, v17
	v_rcp_f32_e32 v32, v17
	v_mul_f32_e32 v17, 0xbfb8aa3b, v15
	v_exp_f32_e32 v17, v17
	v_lshlrev_b32_e32 v22, 16, v33
	v_lshlrev_b32_e32 v38, 16, v23
	v_and_b32_e32 v23, 0xffff0000, v23
	v_add_f32_e32 v17, 1.0, v17
	v_rcp_f32_e32 v33, v17
	v_pk_mul_f32 v[22:23], v[30:31], v[22:23] op_sel:[1,0] op_sel_hi:[0,1]
	v_and_b32_e32 v41, 0xffff0000, v18
	v_lshlrev_b32_e32 v18, 16, v19
	v_and_b32_e32 v19, 0xffff0000, v19
	v_pk_fma_f32 v[22:23], v[30:31], v[38:39], v[22:23]
	v_pk_mul_f32 v[14:15], v[32:33], v[14:15]
	v_pk_fma_f32 v[18:19], v[0:1], v[18:19], v[22:23] op_sel_hi:[0,1,1]
	v_pk_mul_f32 v[18:19], v[14:15], v[18:19]
	v_lshlrev_b32_e32 v14, 16, v24
	v_and_b32_e32 v23, 0xffff0000, v24
	v_lshlrev_b32_e32 v24, 16, v20
	v_and_b32_e32 v25, 0xffff0000, v20
	v_lshlrev_b32_e32 v20, 16, v16
	v_and_b32_e32 v21, 0xffff0000, v16
	v_mul_f32_e32 v16, 0xbfb8aa3b, v20
	v_mul_f32_e32 v17, 0xbfb8aa3b, v21
	v_exp_f32_e32 v16, v16
	v_exp_f32_e32 v17, v17
	v_lshlrev_b32_e32 v22, 16, v34
	v_and_b32_e32 v15, 0xffff0000, v34
	v_add_f32_e32 v16, 1.0, v16
	v_add_f32_e32 v17, 1.0, v17
	v_rcp_f32_e32 v16, v16
	v_rcp_f32_e32 v17, v17
	v_pk_fma_f32 v[36:37], v[0:1], v[40:41], v[36:37] op_sel_hi:[0,1,1]
	v_pk_mul_f32 v[42:43], v[44:45], v[42:43]
	v_pk_mul_f32 v[16:17], v[16:17], v[20:21]
	v_pk_mul_f32 v[20:21], v[30:31], v[22:23] op_sel:[1,0] op_sel_hi:[0,1]
	v_pk_fma_f32 v[14:15], v[30:31], v[14:15], v[20:21]
	v_pk_mul_f32 v[36:37], v[42:43], v[36:37]
	v_pk_fma_f32 v[14:15], v[0:1], v[24:25], v[14:15] op_sel_hi:[0,1,1]
	v_mul_f32_e32 v0, 0xbfb8aa3b, v28
	v_exp_f32_e32 v0, v0
	v_pk_mul_f32 v[16:17], v[16:17], v[14:15]
	v_lshlrev_b32_e32 v30, 16, v2
	v_cvt_pk_bf16_f32 v16, v16, v17
	v_add_f32_e32 v0, 1.0, v0
	v_rcp_f32_e32 v14, v0
	v_mul_f32_e32 v0, 0xbfb8aa3b, v29
	v_exp_f32_e32 v0, v0
	v_and_b32_e32 v31, 0xffff0000, v2
	v_mul_f32_e32 v2, 0xbfb8aa3b, v30
	v_exp_f32_e32 v2, v2
	v_add_f32_e32 v0, 1.0, v0
	v_rcp_f32_e32 v15, v0
	v_lshlrev_b32_e32 v24, 16, v10
	v_add_f32_e32 v2, 1.0, v2
	v_rcp_f32_e32 v32, v2
	v_pk_mul_f32 v[14:15], v[14:15], v[28:29]
	v_mul_f32_e32 v2, 0xbfb8aa3b, v31
	v_pk_mul_f32 v[20:21], v[14:15], v[26:27]
	v_cvt_pk_bf16_f32 v14, v36, v37
	v_cvt_pk_bf16_f32 v15, v18, v19
	v_cvt_pk_bf16_f32 v17, v20, v21
	global_store_dwordx4 v[54:55], v[14:17], off offset:1664
	ds_read_b128 v[20:23], v67
	ds_read_b32 v0, v219 offset:128
	v_exp_f32_e32 v2, v2
	v_and_b32_e32 v27, 0xffff0000, v10
	v_lshlrev_b32_e32 v28, 16, v6
	s_waitcnt lgkmcnt(0)
	v_and_b32_e32 v25, 0xffff0000, v20
	v_max3_f32 v16, v0, v69, v68
	v_sub_f32_e32 v0, v0, v16
	v_exp_f32_e32 v15, v0
	v_sub_f32_e32 v0, v69, v16
	v_exp_f32_e32 v14, v0
	v_sub_f32_e32 v0, v68, v16
	v_exp_f32_e32 v0, v0
	v_add_f32_e32 v2, 1.0, v2
	v_add_f32_e32 v16, v15, v14
	v_rcp_f32_e32 v33, v2
	v_add_f32_e32 v16, v0, v16
	v_rcp_f32_e32 v16, v16
	v_lshlrev_b32_e32 v2, 16, v3
	v_and_b32_e32 v3, 0xffff0000, v3
	v_lshlrev_b32_e32 v26, 16, v20
	v_mul_f32_e32 v0, v0, v16
	v_pk_mul_f32 v[18:19], v[14:15], v[16:17] op_sel_hi:[1,0]
	v_lshlrev_b32_e32 v16, 16, v23
	v_and_b32_e32 v17, 0xffff0000, v13
	v_lshlrev_b32_e32 v14, 16, v13
	v_and_b32_e32 v15, 0xffff0000, v23
	v_pk_mul_f32 v[16:17], v[18:19], v[16:17] op_sel:[1,0] op_sel_hi:[0,1]
	v_pk_fma_f32 v[14:15], v[18:19], v[14:15], v[16:17]
	v_lshlrev_b32_e32 v16, 16, v9
	v_and_b32_e32 v17, 0xffff0000, v9
	v_pk_fma_f32 v[14:15], v[0:1], v[16:17], v[14:15] op_sel_hi:[0,1,1]
	v_lshlrev_b32_e32 v16, 16, v5
	v_and_b32_e32 v17, 0xffff0000, v5
	v_mul_f32_e32 v5, 0xbfb8aa3b, v2
	v_exp_f32_e32 v5, v5
	v_pk_mul_f32 v[26:27], v[18:19], v[26:27] op_sel:[1,0] op_sel_hi:[0,1]
	v_pk_fma_f32 v[24:25], v[18:19], v[24:25], v[26:27]
	v_and_b32_e32 v27, 0xffff0000, v21
	v_add_f32_e32 v5, 1.0, v5
	v_rcp_f32_e32 v20, v5
	v_mul_f32_e32 v5, 0xbfb8aa3b, v3
	v_exp_f32_e32 v5, v5
	v_lshlrev_b32_e32 v10, 16, v21
	v_lshlrev_b32_e32 v26, 16, v11
	v_and_b32_e32 v11, 0xffff0000, v11
	v_add_f32_e32 v5, 1.0, v5
	v_rcp_f32_e32 v21, v5
	v_pk_mul_f32 v[10:11], v[18:19], v[10:11] op_sel:[1,0] op_sel_hi:[0,1]
	v_and_b32_e32 v29, 0xffff0000, v6
	v_lshlrev_b32_e32 v6, 16, v7
	v_and_b32_e32 v7, 0xffff0000, v7
	v_pk_fma_f32 v[10:11], v[18:19], v[26:27], v[10:11]
	v_pk_mul_f32 v[2:3], v[20:21], v[2:3]
	v_pk_fma_f32 v[6:7], v[0:1], v[6:7], v[10:11] op_sel_hi:[0,1,1]
	v_pk_mul_f32 v[6:7], v[2:3], v[6:7]
	v_lshlrev_b32_e32 v2, 16, v12
	v_and_b32_e32 v11, 0xffff0000, v12
	v_lshlrev_b32_e32 v12, 16, v8
	v_and_b32_e32 v13, 0xffff0000, v8
	v_lshlrev_b32_e32 v8, 16, v4
	v_and_b32_e32 v9, 0xffff0000, v4
	v_mul_f32_e32 v4, 0xbfb8aa3b, v8
	v_mul_f32_e32 v5, 0xbfb8aa3b, v9
	v_exp_f32_e32 v4, v4
	v_exp_f32_e32 v5, v5
	v_lshlrev_b32_e32 v10, 16, v22
	v_and_b32_e32 v3, 0xffff0000, v22
	v_add_f32_e32 v4, 1.0, v4
	v_add_f32_e32 v5, 1.0, v5
	v_rcp_f32_e32 v4, v4
	v_rcp_f32_e32 v5, v5
	v_pk_fma_f32 v[24:25], v[0:1], v[28:29], v[24:25] op_sel_hi:[0,1,1]
	v_pk_mul_f32 v[30:31], v[32:33], v[30:31]
	v_pk_mul_f32 v[4:5], v[4:5], v[8:9]
	v_pk_mul_f32 v[8:9], v[18:19], v[10:11] op_sel:[1,0] op_sel_hi:[0,1]
	v_pk_fma_f32 v[2:3], v[18:19], v[2:3], v[8:9]
	v_pk_mul_f32 v[24:25], v[30:31], v[24:25]
	v_pk_fma_f32 v[2:3], v[0:1], v[12:13], v[2:3] op_sel_hi:[0,1,1]
	v_mul_f32_e32 v0, 0xbfb8aa3b, v16
	v_exp_f32_e32 v0, v0
	v_pk_mul_f32 v[4:5], v[4:5], v[2:3]
	v_add_f32_e32 v0, 1.0, v0
	v_rcp_f32_e32 v2, v0
	v_mul_f32_e32 v0, 0xbfb8aa3b, v17
	v_exp_f32_e32 v0, v0
	v_cvt_pk_bf16_f32 v4, v4, v5
	v_add_f32_e32 v0, 1.0, v0
	v_rcp_f32_e32 v3, v0
	s_nop 0
	v_pk_mul_f32 v[2:3], v[2:3], v[16:17]
	s_nop 0
	v_pk_mul_f32 v[8:9], v[2:3], v[14:15]
	v_cvt_pk_bf16_f32 v2, v24, v25
	v_cvt_pk_bf16_f32 v3, v6, v7
	v_cvt_pk_bf16_f32 v5, v8, v9
	global_store_dwordx4 v[56:57], v[2:5], off offset:1664
	s_cbranch_vccz .LBB0_707
